# GEMM K-loops on v_mfma_f32_16x16x32_bf16 (in-place permlane16/32 swap back to the 32x32 layout), ring + saddr DMA, two barriers per K-step
# baseline (speedup 1.0000x reference)
.Lg161_loop:
	s_add_u32 s51, s50, 0x10000
	s_sub_u32 s53, s51, 0x28000
	s_cmp_ge_u32 s51, 0x28000
	s_cselect_b32 s51, s53, s51
	s_add_u32 s52, s49, 0x20000
	s_sub_u32 s53, s52, 0x28000
	s_cmp_ge_u32 s52, 0x28000
	s_cselect_b32 s52, s53, s52
	v_add_u32_e32 v137, s50, v135
	s_waitcnt lgkmcnt(4)
	s_waitcnt lgkmcnt(3)
	v_mfma_f32_16x16x32_bf16 v[112:115], v[164:167], v[224:227], v[112:115]
	v_mfma_f32_16x16x32_bf16 v[120:123], v[168:171], v[224:227], v[120:123]
	v_mfma_f32_16x16x32_bf16 v[96:99], v[172:175], v[224:227], v[96:99]
	v_mfma_f32_16x16x32_bf16 v[104:107], v[176:179], v[224:227], v[104:107]
	s_add_u32 m0, s51, s48
	s_nop 0
	global_load_lds_dwordx4 v139, s[64:65]
	s_add_u32 s64, s64, 0x80
	s_addc_u32 s65, s65, 0
	ds_read_b128 v[224:227], v136 offset:8192
	ds_read_b128 v[180:183], v137
	s_waitcnt lgkmcnt(4)
	v_mfma_f32_16x16x32_bf16 v[116:119], v[164:167], v[228:231], v[116:119]
	v_mfma_f32_16x16x32_bf16 v[124:127], v[168:171], v[228:231], v[124:127]
	v_mfma_f32_16x16x32_bf16 v[100:103], v[172:175], v[228:231], v[100:103]
	v_mfma_f32_16x16x32_bf16 v[108:111], v[176:179], v[228:231], v[108:111]
	s_add_u32 s53, s51, s48
	s_add_u32 m0, s53, 0x2000
	s_nop 0
	global_load_lds_dwordx4 v139, s[66:67]
	s_add_u32 s66, s66, 0x80
	s_addc_u32 s67, s67, 0
	ds_read_b128 v[228:231], v136 offset:10240
	ds_read_b128 v[212:215], v137 offset:2048
	s_waitcnt lgkmcnt(5)
	v_mfma_f32_16x16x32_bf16 v[80:83], v[164:167], v[232:235], v[80:83]
	v_mfma_f32_16x16x32_bf16 v[88:91], v[168:171], v[232:235], v[88:91]
	v_mfma_f32_16x16x32_bf16 v[64:67], v[172:175], v[232:235], v[64:67]
	v_mfma_f32_16x16x32_bf16 v[72:75], v[176:179], v[232:235], v[72:75]
	s_add_u32 s53, s51, s48
	s_add_u32 m0, s53, 0x4000
	s_nop 0
	global_load_lds_dwordx4 v139, s[68:69]
	s_add_u32 s68, s68, 0x80
	s_addc_u32 s69, s69, 0
	ds_read_b128 v[232:235], v136 offset:12288
	ds_read_b128 v[216:219], v137 offset:4096
	s_waitcnt lgkmcnt(6)
	v_mfma_f32_16x16x32_bf16 v[84:87], v[164:167], v[236:239], v[84:87]
	v_mfma_f32_16x16x32_bf16 v[92:95], v[168:171], v[236:239], v[92:95]
	v_mfma_f32_16x16x32_bf16 v[68:71], v[172:175], v[236:239], v[68:71]
	v_mfma_f32_16x16x32_bf16 v[76:79], v[176:179], v[236:239], v[76:79]
	s_add_u32 s53, s51, s48
	s_add_u32 m0, s53, 0x6000
	s_nop 0
	global_load_lds_dwordx4 v139, s[70:71]
	s_add_u32 s70, s70, 0x80
	s_addc_u32 s71, s71, 0
	ds_read_b128 v[236:239], v136 offset:14336
	ds_read_b128 v[220:223], v137 offset:6144
	v_add_u32_e32 v136, s49, v133
	s_waitcnt lgkmcnt(7)
	v_mfma_f32_16x16x32_bf16 v[48:51], v[164:167], v[224:227], v[48:51]
	v_mfma_f32_16x16x32_bf16 v[56:59], v[168:171], v[224:227], v[56:59]
	v_mfma_f32_16x16x32_bf16 v[32:35], v[172:175], v[224:227], v[32:35]
	v_mfma_f32_16x16x32_bf16 v[40:43], v[176:179], v[224:227], v[40:43]
	s_add_u32 m0, s52, s48
	s_nop 0
	global_load_lds_dwordx4 v138, s[56:57]
	s_add_u32 s56, s56, 0x80
	s_addc_u32 s57, s57, 0
	ds_read_b128 v[224:227], v136
	s_waitcnt lgkmcnt(6)
	v_mfma_f32_16x16x32_bf16 v[52:55], v[164:167], v[228:231], v[52:55]
	v_mfma_f32_16x16x32_bf16 v[60:63], v[168:171], v[228:231], v[60:63]
	v_mfma_f32_16x16x32_bf16 v[36:39], v[172:175], v[228:231], v[36:39]
	v_mfma_f32_16x16x32_bf16 v[44:47], v[176:179], v[228:231], v[44:47]
	s_add_u32 s53, s52, s48
	s_add_u32 m0, s53, 0x2000
	s_nop 0
	global_load_lds_dwordx4 v138, s[58:59]
	s_add_u32 s58, s58, 0x80
	s_addc_u32 s59, s59, 0
	ds_read_b128 v[228:231], v136 offset:2048
	s_waitcnt lgkmcnt(5)
	v_mfma_f32_16x16x32_bf16 v[16:19], v[164:167], v[232:235], v[16:19]
	v_mfma_f32_16x16x32_bf16 v[24:27], v[168:171], v[232:235], v[24:27]
	v_mfma_f32_16x16x32_bf16 v[0:3], v[172:175], v[232:235], v[0:3]
	v_mfma_f32_16x16x32_bf16 v[8:11], v[176:179], v[232:235], v[8:11]
	s_add_u32 s53, s52, s48
	s_add_u32 m0, s53, 0x4000
	s_nop 0
	global_load_lds_dwordx4 v138, s[60:61]
	s_add_u32 s60, s60, 0x80
	s_addc_u32 s61, s61, 0
	ds_read_b128 v[232:235], v136 offset:4096
	s_waitcnt lgkmcnt(4)
	v_mfma_f32_16x16x32_bf16 v[20:23], v[164:167], v[236:239], v[20:23]
	v_mfma_f32_16x16x32_bf16 v[28:31], v[168:171], v[236:239], v[28:31]
	v_mfma_f32_16x16x32_bf16 v[4:7], v[172:175], v[236:239], v[4:7]
	v_mfma_f32_16x16x32_bf16 v[12:15], v[176:179], v[236:239], v[12:15]
	s_add_u32 s53, s52, s48
	s_add_u32 m0, s53, 0x6000
	s_nop 0
	global_load_lds_dwordx4 v138, s[62:63]
	s_add_u32 s62, s62, 0x80
	s_addc_u32 s63, s63, 0
	ds_read_b128 v[236:239], v136 offset:6144
	s_waitcnt lgkmcnt(4)
	s_waitcnt lgkmcnt(3)
	v_mfma_f32_16x16x32_bf16 v[112:115], v[180:183], v[224:227], v[112:115]
	v_mfma_f32_16x16x32_bf16 v[120:123], v[212:215], v[224:227], v[120:123]
	v_mfma_f32_16x16x32_bf16 v[96:99], v[216:219], v[224:227], v[96:99]
	v_mfma_f32_16x16x32_bf16 v[104:107], v[220:223], v[224:227], v[104:107]
	ds_read_b128 v[224:227], v136 offset:8192
	s_waitcnt lgkmcnt(3)
	v_mfma_f32_16x16x32_bf16 v[116:119], v[180:183], v[228:231], v[116:119]
	v_mfma_f32_16x16x32_bf16 v[124:127], v[212:215], v[228:231], v[124:127]
	v_mfma_f32_16x16x32_bf16 v[100:103], v[216:219], v[228:231], v[100:103]
	v_mfma_f32_16x16x32_bf16 v[108:111], v[220:223], v[228:231], v[108:111]
	ds_read_b128 v[228:231], v136 offset:10240
	s_waitcnt lgkmcnt(3)
	v_mfma_f32_16x16x32_bf16 v[80:83], v[180:183], v[232:235], v[80:83]
	v_mfma_f32_16x16x32_bf16 v[88:91], v[212:215], v[232:235], v[88:91]
	v_mfma_f32_16x16x32_bf16 v[64:67], v[216:219], v[232:235], v[64:67]
	v_mfma_f32_16x16x32_bf16 v[72:75], v[220:223], v[232:235], v[72:75]
	ds_read_b128 v[232:235], v136 offset:12288
	s_waitcnt lgkmcnt(3)
	v_mfma_f32_16x16x32_bf16 v[84:87], v[180:183], v[236:239], v[84:87]
	v_mfma_f32_16x16x32_bf16 v[92:95], v[212:215], v[236:239], v[92:95]
	v_mfma_f32_16x16x32_bf16 v[68:71], v[216:219], v[236:239], v[68:71]
	v_mfma_f32_16x16x32_bf16 v[76:79], v[220:223], v[236:239], v[76:79]
	ds_read_b128 v[236:239], v136 offset:14336
	s_waitcnt lgkmcnt(3)
	v_mfma_f32_16x16x32_bf16 v[48:51], v[180:183], v[224:227], v[48:51]
	v_mfma_f32_16x16x32_bf16 v[56:59], v[212:215], v[224:227], v[56:59]
	v_mfma_f32_16x16x32_bf16 v[32:35], v[216:219], v[224:227], v[32:35]
	v_mfma_f32_16x16x32_bf16 v[40:43], v[220:223], v[224:227], v[40:43]
	s_waitcnt lgkmcnt(2)
	v_mfma_f32_16x16x32_bf16 v[52:55], v[180:183], v[228:231], v[52:55]
	v_mfma_f32_16x16x32_bf16 v[60:63], v[212:215], v[228:231], v[60:63]
	v_mfma_f32_16x16x32_bf16 v[36:39], v[216:219], v[228:231], v[36:39]
	v_mfma_f32_16x16x32_bf16 v[44:47], v[220:223], v[228:231], v[44:47]
	s_waitcnt lgkmcnt(0)
	s_add_u32 s4, s4, 0x80
	s_addc_u32 s5, s5, 0
	s_add_u32 s49, s49, 0x10000
	s_sub_u32 s53, s49, 0x28000
	s_cmp_ge_u32 s49, 0x28000
	s_cselect_b32 s49, s53, s49
	s_mov_b32 s50, s51
	s_waitcnt vmcnt(4)
	s_barrier
	s_barrier
	v_add_u32_e32 v137, s50, v134
	v_add_u32_e32 v136, s49, v132
	ds_read_b128 v[164:167], v137
	ds_read_b128 v[168:171], v137 offset:2048
	ds_read_b128 v[172:175], v137 offset:4096
	ds_read_b128 v[176:179], v137 offset:6144
	ds_read_b128 v[224:227], v136
	ds_read_b128 v[228:231], v136 offset:2048
	v_mfma_f32_16x16x32_bf16 v[16:19], v[180:183], v[232:235], v[16:19]
	v_mfma_f32_16x16x32_bf16 v[24:27], v[212:215], v[232:235], v[24:27]
	v_mfma_f32_16x16x32_bf16 v[0:3], v[216:219], v[232:235], v[0:3]
	v_mfma_f32_16x16x32_bf16 v[8:11], v[220:223], v[232:235], v[8:11]
	ds_read_b128 v[232:235], v136 offset:4096
	v_mfma_f32_16x16x32_bf16 v[20:23], v[180:183], v[236:239], v[20:23]
	v_mfma_f32_16x16x32_bf16 v[28:31], v[212:215], v[236:239], v[28:31]
	v_mfma_f32_16x16x32_bf16 v[4:7], v[216:219], v[236:239], v[4:7]
	v_mfma_f32_16x16x32_bf16 v[12:15], v[220:223], v[236:239], v[12:15]
	ds_read_b128 v[236:239], v136 offset:6144
	s_cmpk_lg_i32 s4, 0xf00
	s_cbranch_scc1 .Lg161_loop
	s_add_u32 s51, s50, 0x10000
	s_sub_u32 s53, s51, 0x28000
	s_cmp_ge_u32 s51, 0x28000
	s_cselect_b32 s51, s53, s51
	v_add_u32_e32 v137, s50, v135
	s_waitcnt lgkmcnt(4)
	s_waitcnt lgkmcnt(3)
	v_mfma_f32_16x16x32_bf16 v[112:115], v[164:167], v[224:227], v[112:115]
	v_mfma_f32_16x16x32_bf16 v[120:123], v[168:171], v[224:227], v[120:123]
	v_mfma_f32_16x16x32_bf16 v[96:99], v[172:175], v[224:227], v[96:99]
	v_mfma_f32_16x16x32_bf16 v[104:107], v[176:179], v[224:227], v[104:107]
	s_add_u32 m0, s51, s48
	s_nop 0
	global_load_lds_dwordx4 v139, s[64:65]
	s_add_u32 s64, s64, 0x80
	s_addc_u32 s65, s65, 0
	ds_read_b128 v[224:227], v136 offset:8192
	ds_read_b128 v[180:183], v137
	s_waitcnt lgkmcnt(4)
	v_mfma_f32_16x16x32_bf16 v[116:119], v[164:167], v[228:231], v[116:119]
	v_mfma_f32_16x16x32_bf16 v[124:127], v[168:171], v[228:231], v[124:127]
	v_mfma_f32_16x16x32_bf16 v[100:103], v[172:175], v[228:231], v[100:103]
	v_mfma_f32_16x16x32_bf16 v[108:111], v[176:179], v[228:231], v[108:111]
	s_add_u32 s53, s51, s48
	s_add_u32 m0, s53, 0x2000
	s_nop 0
	global_load_lds_dwordx4 v139, s[66:67]
	s_add_u32 s66, s66, 0x80
	s_addc_u32 s67, s67, 0
	ds_read_b128 v[228:231], v136 offset:10240
	ds_read_b128 v[212:215], v137 offset:2048
	s_waitcnt lgkmcnt(5)
	v_mfma_f32_16x16x32_bf16 v[80:83], v[164:167], v[232:235], v[80:83]
	v_mfma_f32_16x16x32_bf16 v[88:91], v[168:171], v[232:235], v[88:91]
	v_mfma_f32_16x16x32_bf16 v[64:67], v[172:175], v[232:235], v[64:67]
	v_mfma_f32_16x16x32_bf16 v[72:75], v[176:179], v[232:235], v[72:75]
	s_add_u32 s53, s51, s48
	s_add_u32 m0, s53, 0x4000
	s_nop 0
	global_load_lds_dwordx4 v139, s[68:69]
	s_add_u32 s68, s68, 0x80
	s_addc_u32 s69, s69, 0
	ds_read_b128 v[232:235], v136 offset:12288
	ds_read_b128 v[216:219], v137 offset:4096
	s_waitcnt lgkmcnt(6)
	v_mfma_f32_16x16x32_bf16 v[84:87], v[164:167], v[236:239], v[84:87]
	v_mfma_f32_16x16x32_bf16 v[92:95], v[168:171], v[236:239], v[92:95]
	v_mfma_f32_16x16x32_bf16 v[68:71], v[172:175], v[236:239], v[68:71]
	v_mfma_f32_16x16x32_bf16 v[76:79], v[176:179], v[236:239], v[76:79]
	s_add_u32 s53, s51, s48
	s_add_u32 m0, s53, 0x6000
	s_nop 0
	global_load_lds_dwordx4 v139, s[70:71]
	s_add_u32 s70, s70, 0x80
	s_addc_u32 s71, s71, 0
	ds_read_b128 v[236:239], v136 offset:14336
	ds_read_b128 v[220:223], v137 offset:6144
	v_add_u32_e32 v136, s49, v133
	s_waitcnt lgkmcnt(7)
	v_mfma_f32_16x16x32_bf16 v[48:51], v[164:167], v[224:227], v[48:51]
	v_mfma_f32_16x16x32_bf16 v[56:59], v[168:171], v[224:227], v[56:59]
	v_mfma_f32_16x16x32_bf16 v[32:35], v[172:175], v[224:227], v[32:35]
	v_mfma_f32_16x16x32_bf16 v[40:43], v[176:179], v[224:227], v[40:43]
	ds_read_b128 v[224:227], v136
	s_waitcnt lgkmcnt(6)
	v_mfma_f32_16x16x32_bf16 v[52:55], v[164:167], v[228:231], v[52:55]
	v_mfma_f32_16x16x32_bf16 v[60:63], v[168:171], v[228:231], v[60:63]
	v_mfma_f32_16x16x32_bf16 v[36:39], v[172:175], v[228:231], v[36:39]
	v_mfma_f32_16x16x32_bf16 v[44:47], v[176:179], v[228:231], v[44:47]
	ds_read_b128 v[228:231], v136 offset:2048
	s_waitcnt lgkmcnt(5)
	v_mfma_f32_16x16x32_bf16 v[16:19], v[164:167], v[232:235], v[16:19]
	v_mfma_f32_16x16x32_bf16 v[24:27], v[168:171], v[232:235], v[24:27]
	v_mfma_f32_16x16x32_bf16 v[0:3], v[172:175], v[232:235], v[0:3]
	v_mfma_f32_16x16x32_bf16 v[8:11], v[176:179], v[232:235], v[8:11]
	ds_read_b128 v[232:235], v136 offset:4096
	s_waitcnt lgkmcnt(4)
	v_mfma_f32_16x16x32_bf16 v[20:23], v[164:167], v[236:239], v[20:23]
	v_mfma_f32_16x16x32_bf16 v[28:31], v[168:171], v[236:239], v[28:31]
	v_mfma_f32_16x16x32_bf16 v[4:7], v[172:175], v[236:239], v[4:7]
	v_mfma_f32_16x16x32_bf16 v[12:15], v[176:179], v[236:239], v[12:15]
	ds_read_b128 v[236:239], v136 offset:6144
	s_waitcnt lgkmcnt(4)
	s_waitcnt lgkmcnt(3)
	v_mfma_f32_16x16x32_bf16 v[112:115], v[180:183], v[224:227], v[112:115]
	v_mfma_f32_16x16x32_bf16 v[120:123], v[212:215], v[224:227], v[120:123]
	v_mfma_f32_16x16x32_bf16 v[96:99], v[216:219], v[224:227], v[96:99]
	v_mfma_f32_16x16x32_bf16 v[104:107], v[220:223], v[224:227], v[104:107]
	ds_read_b128 v[224:227], v136 offset:8192
	s_waitcnt lgkmcnt(3)
	v_mfma_f32_16x16x32_bf16 v[116:119], v[180:183], v[228:231], v[116:119]
	v_mfma_f32_16x16x32_bf16 v[124:127], v[212:215], v[228:231], v[124:127]
	v_mfma_f32_16x16x32_bf16 v[100:103], v[216:219], v[228:231], v[100:103]
	v_mfma_f32_16x16x32_bf16 v[108:111], v[220:223], v[228:231], v[108:111]
	ds_read_b128 v[228:231], v136 offset:10240
	s_waitcnt lgkmcnt(3)
	v_mfma_f32_16x16x32_bf16 v[80:83], v[180:183], v[232:235], v[80:83]
	v_mfma_f32_16x16x32_bf16 v[88:91], v[212:215], v[232:235], v[88:91]
	v_mfma_f32_16x16x32_bf16 v[64:67], v[216:219], v[232:235], v[64:67]
	v_mfma_f32_16x16x32_bf16 v[72:75], v[220:223], v[232:235], v[72:75]
	ds_read_b128 v[232:235], v136 offset:12288
	s_waitcnt lgkmcnt(3)
	v_mfma_f32_16x16x32_bf16 v[84:87], v[180:183], v[236:239], v[84:87]
	v_mfma_f32_16x16x32_bf16 v[92:95], v[212:215], v[236:239], v[92:95]
	v_mfma_f32_16x16x32_bf16 v[68:71], v[216:219], v[236:239], v[68:71]
	v_mfma_f32_16x16x32_bf16 v[76:79], v[220:223], v[236:239], v[76:79]
	ds_read_b128 v[236:239], v136 offset:14336
	s_waitcnt lgkmcnt(3)
	v_mfma_f32_16x16x32_bf16 v[48:51], v[180:183], v[224:227], v[48:51]
	v_mfma_f32_16x16x32_bf16 v[56:59], v[212:215], v[224:227], v[56:59]
	v_mfma_f32_16x16x32_bf16 v[32:35], v[216:219], v[224:227], v[32:35]
	v_mfma_f32_16x16x32_bf16 v[40:43], v[220:223], v[224:227], v[40:43]
	s_waitcnt lgkmcnt(2)
	v_mfma_f32_16x16x32_bf16 v[52:55], v[180:183], v[228:231], v[52:55]
	v_mfma_f32_16x16x32_bf16 v[60:63], v[212:215], v[228:231], v[60:63]
	v_mfma_f32_16x16x32_bf16 v[36:39], v[216:219], v[228:231], v[36:39]
	v_mfma_f32_16x16x32_bf16 v[44:47], v[220:223], v[228:231], v[44:47]
	s_waitcnt lgkmcnt(0)
	s_add_u32 s4, s4, 0x80
	s_addc_u32 s5, s5, 0
	s_add_u32 s49, s49, 0x10000
	s_sub_u32 s53, s49, 0x28000
	s_cmp_ge_u32 s49, 0x28000
	s_cselect_b32 s49, s53, s49
	s_mov_b32 s50, s51
	s_waitcnt vmcnt(0)
	s_barrier
	s_barrier
	v_add_u32_e32 v137, s50, v134
	v_add_u32_e32 v136, s49, v132
	ds_read_b128 v[164:167], v137
	ds_read_b128 v[168:171], v137 offset:2048
	ds_read_b128 v[172:175], v137 offset:4096
	ds_read_b128 v[176:179], v137 offset:6144
	ds_read_b128 v[224:227], v136
	ds_read_b128 v[228:231], v136 offset:2048
	v_mfma_f32_16x16x32_bf16 v[16:19], v[180:183], v[232:235], v[16:19]
	v_mfma_f32_16x16x32_bf16 v[24:27], v[212:215], v[232:235], v[24:27]
	v_mfma_f32_16x16x32_bf16 v[0:3], v[216:219], v[232:235], v[0:3]
	v_mfma_f32_16x16x32_bf16 v[8:11], v[220:223], v[232:235], v[8:11]
	ds_read_b128 v[232:235], v136 offset:4096
	v_mfma_f32_16x16x32_bf16 v[20:23], v[180:183], v[236:239], v[20:23]
	v_mfma_f32_16x16x32_bf16 v[28:31], v[212:215], v[236:239], v[28:31]
	v_mfma_f32_16x16x32_bf16 v[4:7], v[216:219], v[236:239], v[4:7]
	v_mfma_f32_16x16x32_bf16 v[12:15], v[220:223], v[236:239], v[12:15]
	ds_read_b128 v[236:239], v136 offset:6144
	v_add_u32_e32 v137, s50, v135
	s_waitcnt lgkmcnt(4)
	s_waitcnt lgkmcnt(3)
	v_mfma_f32_16x16x32_bf16 v[112:115], v[164:167], v[224:227], v[112:115]
	v_mfma_f32_16x16x32_bf16 v[120:123], v[168:171], v[224:227], v[120:123]
	v_mfma_f32_16x16x32_bf16 v[96:99], v[172:175], v[224:227], v[96:99]
	v_mfma_f32_16x16x32_bf16 v[104:107], v[176:179], v[224:227], v[104:107]
	ds_read_b128 v[224:227], v136 offset:8192
	ds_read_b128 v[180:183], v137
	s_waitcnt lgkmcnt(4)
	v_mfma_f32_16x16x32_bf16 v[116:119], v[164:167], v[228:231], v[116:119]
	v_mfma_f32_16x16x32_bf16 v[124:127], v[168:171], v[228:231], v[124:127]
	v_mfma_f32_16x16x32_bf16 v[100:103], v[172:175], v[228:231], v[100:103]
	v_mfma_f32_16x16x32_bf16 v[108:111], v[176:179], v[228:231], v[108:111]
	ds_read_b128 v[228:231], v136 offset:10240
	ds_read_b128 v[212:215], v137 offset:2048
	s_waitcnt lgkmcnt(5)
	v_mfma_f32_16x16x32_bf16 v[80:83], v[164:167], v[232:235], v[80:83]
	v_mfma_f32_16x16x32_bf16 v[88:91], v[168:171], v[232:235], v[88:91]
	v_mfma_f32_16x16x32_bf16 v[64:67], v[172:175], v[232:235], v[64:67]
	v_mfma_f32_16x16x32_bf16 v[72:75], v[176:179], v[232:235], v[72:75]
	ds_read_b128 v[232:235], v136 offset:12288
	ds_read_b128 v[216:219], v137 offset:4096
	s_waitcnt lgkmcnt(6)
	v_mfma_f32_16x16x32_bf16 v[84:87], v[164:167], v[236:239], v[84:87]
	v_mfma_f32_16x16x32_bf16 v[92:95], v[168:171], v[236:239], v[92:95]
	v_mfma_f32_16x16x32_bf16 v[68:71], v[172:175], v[236:239], v[68:71]
	v_mfma_f32_16x16x32_bf16 v[76:79], v[176:179], v[236:239], v[76:79]
	ds_read_b128 v[236:239], v136 offset:14336
	ds_read_b128 v[220:223], v137 offset:6144
	v_add_u32_e32 v136, s49, v133
	s_waitcnt lgkmcnt(7)
	v_mfma_f32_16x16x32_bf16 v[48:51], v[164:167], v[224:227], v[48:51]
	v_mfma_f32_16x16x32_bf16 v[56:59], v[168:171], v[224:227], v[56:59]
	v_mfma_f32_16x16x32_bf16 v[32:35], v[172:175], v[224:227], v[32:35]
	v_mfma_f32_16x16x32_bf16 v[40:43], v[176:179], v[224:227], v[40:43]
	ds_read_b128 v[224:227], v136
	s_waitcnt lgkmcnt(6)
	v_mfma_f32_16x16x32_bf16 v[52:55], v[164:167], v[228:231], v[52:55]
	v_mfma_f32_16x16x32_bf16 v[60:63], v[168:171], v[228:231], v[60:63]
	v_mfma_f32_16x16x32_bf16 v[36:39], v[172:175], v[228:231], v[36:39]
	v_mfma_f32_16x16x32_bf16 v[44:47], v[176:179], v[228:231], v[44:47]
	ds_read_b128 v[228:231], v136 offset:2048
	s_waitcnt lgkmcnt(5)
	v_mfma_f32_16x16x32_bf16 v[16:19], v[164:167], v[232:235], v[16:19]
	v_mfma_f32_16x16x32_bf16 v[24:27], v[168:171], v[232:235], v[24:27]
	v_mfma_f32_16x16x32_bf16 v[0:3], v[172:175], v[232:235], v[0:3]
	v_mfma_f32_16x16x32_bf16 v[8:11], v[176:179], v[232:235], v[8:11]
	ds_read_b128 v[232:235], v136 offset:4096
	s_waitcnt lgkmcnt(4)
	v_mfma_f32_16x16x32_bf16 v[20:23], v[164:167], v[236:239], v[20:23]
	v_mfma_f32_16x16x32_bf16 v[28:31], v[168:171], v[236:239], v[28:31]
	v_mfma_f32_16x16x32_bf16 v[4:7], v[172:175], v[236:239], v[4:7]
	v_mfma_f32_16x16x32_bf16 v[12:15], v[176:179], v[236:239], v[12:15]
	ds_read_b128 v[236:239], v136 offset:6144
	s_waitcnt lgkmcnt(4)
	s_waitcnt lgkmcnt(3)
	v_mfma_f32_16x16x32_bf16 v[112:115], v[180:183], v[224:227], v[112:115]
	v_mfma_f32_16x16x32_bf16 v[120:123], v[212:215], v[224:227], v[120:123]
	v_mfma_f32_16x16x32_bf16 v[96:99], v[216:219], v[224:227], v[96:99]
	v_mfma_f32_16x16x32_bf16 v[104:107], v[220:223], v[224:227], v[104:107]
	ds_read_b128 v[224:227], v136 offset:8192
	s_waitcnt lgkmcnt(3)
	v_mfma_f32_16x16x32_bf16 v[116:119], v[180:183], v[228:231], v[116:119]
	v_mfma_f32_16x16x32_bf16 v[124:127], v[212:215], v[228:231], v[124:127]
	v_mfma_f32_16x16x32_bf16 v[100:103], v[216:219], v[228:231], v[100:103]
	v_mfma_f32_16x16x32_bf16 v[108:111], v[220:223], v[228:231], v[108:111]
	ds_read_b128 v[228:231], v136 offset:10240
	s_waitcnt lgkmcnt(3)
	v_mfma_f32_16x16x32_bf16 v[80:83], v[180:183], v[232:235], v[80:83]
	v_mfma_f32_16x16x32_bf16 v[88:91], v[212:215], v[232:235], v[88:91]
	v_mfma_f32_16x16x32_bf16 v[64:67], v[216:219], v[232:235], v[64:67]
	v_mfma_f32_16x16x32_bf16 v[72:75], v[220:223], v[232:235], v[72:75]
	ds_read_b128 v[232:235], v136 offset:12288
	s_waitcnt lgkmcnt(3)
	v_mfma_f32_16x16x32_bf16 v[84:87], v[180:183], v[236:239], v[84:87]
	v_mfma_f32_16x16x32_bf16 v[92:95], v[212:215], v[236:239], v[92:95]
	v_mfma_f32_16x16x32_bf16 v[68:71], v[216:219], v[236:239], v[68:71]
	v_mfma_f32_16x16x32_bf16 v[76:79], v[220:223], v[236:239], v[76:79]
	ds_read_b128 v[236:239], v136 offset:14336
	s_waitcnt lgkmcnt(3)
	v_mfma_f32_16x16x32_bf16 v[48:51], v[180:183], v[224:227], v[48:51]
	v_mfma_f32_16x16x32_bf16 v[56:59], v[212:215], v[224:227], v[56:59]
	v_mfma_f32_16x16x32_bf16 v[32:35], v[216:219], v[224:227], v[32:35]
	v_mfma_f32_16x16x32_bf16 v[40:43], v[220:223], v[224:227], v[40:43]
	s_waitcnt lgkmcnt(2)
	v_mfma_f32_16x16x32_bf16 v[52:55], v[180:183], v[228:231], v[52:55]
	v_mfma_f32_16x16x32_bf16 v[60:63], v[212:215], v[228:231], v[60:63]
	v_mfma_f32_16x16x32_bf16 v[36:39], v[216:219], v[228:231], v[36:39]
	v_mfma_f32_16x16x32_bf16 v[44:47], v[220:223], v[228:231], v[44:47]
	s_waitcnt lgkmcnt(0)
	s_waitcnt vmcnt(0)
	s_barrier
	s_barrier
	v_mfma_f32_16x16x32_bf16 v[16:19], v[180:183], v[232:235], v[16:19]
	v_mfma_f32_16x16x32_bf16 v[24:27], v[212:215], v[232:235], v[24:27]
	v_mfma_f32_16x16x32_bf16 v[0:3], v[216:219], v[232:235], v[0:3]
	v_mfma_f32_16x16x32_bf16 v[8:11], v[220:223], v[232:235], v[8:11]
	v_mfma_f32_16x16x32_bf16 v[20:23], v[180:183], v[236:239], v[20:23]
	v_mfma_f32_16x16x32_bf16 v[28:31], v[212:215], v[236:239], v[28:31]
	v_mfma_f32_16x16x32_bf16 v[4:7], v[216:219], v[236:239], v[4:7]
	v_mfma_f32_16x16x32_bf16 v[12:15], v[220:223], v[236:239], v[12:15]
	s_nop 15
	v_permlane16_swap_b32_e32 v112, v116
	v_permlane16_swap_b32_e32 v113, v117
	v_permlane16_swap_b32_e32 v114, v118
	v_permlane16_swap_b32_e32 v115, v119
	v_permlane16_swap_b32_e32 v120, v124
	v_permlane16_swap_b32_e32 v121, v125
	v_permlane16_swap_b32_e32 v122, v126
	v_permlane16_swap_b32_e32 v123, v127
	v_permlane16_swap_b32_e32 v96, v100
	v_permlane16_swap_b32_e32 v97, v101
	v_permlane16_swap_b32_e32 v98, v102
	v_permlane16_swap_b32_e32 v99, v103
	v_permlane16_swap_b32_e32 v104, v108
	v_permlane16_swap_b32_e32 v105, v109
	v_permlane16_swap_b32_e32 v106, v110
	v_permlane16_swap_b32_e32 v107, v111
	v_permlane16_swap_b32_e32 v80, v84
	v_permlane16_swap_b32_e32 v81, v85
	v_permlane16_swap_b32_e32 v82, v86
	v_permlane16_swap_b32_e32 v83, v87
	v_permlane16_swap_b32_e32 v88, v92
	v_permlane16_swap_b32_e32 v89, v93
	v_permlane16_swap_b32_e32 v90, v94
	v_permlane16_swap_b32_e32 v91, v95
	v_permlane16_swap_b32_e32 v64, v68
	v_permlane16_swap_b32_e32 v65, v69
	v_permlane16_swap_b32_e32 v66, v70
	v_permlane16_swap_b32_e32 v67, v71
	v_permlane16_swap_b32_e32 v72, v76
	v_permlane16_swap_b32_e32 v73, v77
	v_permlane16_swap_b32_e32 v74, v78
	v_permlane16_swap_b32_e32 v75, v79
	v_permlane16_swap_b32_e32 v48, v52
	v_permlane16_swap_b32_e32 v49, v53
	v_permlane16_swap_b32_e32 v50, v54
	v_permlane16_swap_b32_e32 v51, v55
	v_permlane16_swap_b32_e32 v56, v60
	v_permlane16_swap_b32_e32 v57, v61
	v_permlane16_swap_b32_e32 v58, v62
	v_permlane16_swap_b32_e32 v59, v63
	v_permlane16_swap_b32_e32 v32, v36
	v_permlane16_swap_b32_e32 v33, v37
	v_permlane16_swap_b32_e32 v34, v38
	v_permlane16_swap_b32_e32 v35, v39
	v_permlane16_swap_b32_e32 v40, v44
	v_permlane16_swap_b32_e32 v41, v45
	v_permlane16_swap_b32_e32 v42, v46
	v_permlane16_swap_b32_e32 v43, v47
	v_permlane16_swap_b32_e32 v16, v20
	v_permlane16_swap_b32_e32 v17, v21
	v_permlane16_swap_b32_e32 v18, v22
	v_permlane16_swap_b32_e32 v19, v23
	v_permlane16_swap_b32_e32 v24, v28
	v_permlane16_swap_b32_e32 v25, v29
	v_permlane16_swap_b32_e32 v26, v30
	v_permlane16_swap_b32_e32 v27, v31
	v_permlane16_swap_b32_e32 v0, v4
	v_permlane16_swap_b32_e32 v1, v5
	v_permlane16_swap_b32_e32 v2, v6
	v_permlane16_swap_b32_e32 v3, v7
	v_permlane16_swap_b32_e32 v8, v12
	v_permlane16_swap_b32_e32 v9, v13
	v_permlane16_swap_b32_e32 v10, v14
	v_permlane16_swap_b32_e32 v11, v15
	v_permlane32_swap_b32_e32 v112, v116
	v_permlane32_swap_b32_e32 v113, v117
	v_permlane32_swap_b32_e32 v114, v118
	v_permlane32_swap_b32_e32 v115, v119
	v_permlane32_swap_b32_e32 v120, v124
	v_permlane32_swap_b32_e32 v121, v125
	v_permlane32_swap_b32_e32 v122, v126
	v_permlane32_swap_b32_e32 v123, v127
	v_permlane32_swap_b32_e32 v96, v100
	v_permlane32_swap_b32_e32 v97, v101
	v_permlane32_swap_b32_e32 v98, v102
	v_permlane32_swap_b32_e32 v99, v103
	v_permlane32_swap_b32_e32 v104, v108
	v_permlane32_swap_b32_e32 v105, v109
	v_permlane32_swap_b32_e32 v106, v110
	v_permlane32_swap_b32_e32 v107, v111
	v_permlane32_swap_b32_e32 v80, v84
	v_permlane32_swap_b32_e32 v81, v85
	v_permlane32_swap_b32_e32 v82, v86
	v_permlane32_swap_b32_e32 v83, v87
	v_permlane32_swap_b32_e32 v88, v92
	v_permlane32_swap_b32_e32 v89, v93
	v_permlane32_swap_b32_e32 v90, v94
	v_permlane32_swap_b32_e32 v91, v95
	v_permlane32_swap_b32_e32 v64, v68
	v_permlane32_swap_b32_e32 v65, v69
	v_permlane32_swap_b32_e32 v66, v70
	v_permlane32_swap_b32_e32 v67, v71
	v_permlane32_swap_b32_e32 v72, v76
	v_permlane32_swap_b32_e32 v73, v77
	v_permlane32_swap_b32_e32 v74, v78
	v_permlane32_swap_b32_e32 v75, v79
	v_permlane32_swap_b32_e32 v48, v52
	v_permlane32_swap_b32_e32 v49, v53
	v_permlane32_swap_b32_e32 v50, v54
	v_permlane32_swap_b32_e32 v51, v55
	v_permlane32_swap_b32_e32 v56, v60
	v_permlane32_swap_b32_e32 v57, v61
	v_permlane32_swap_b32_e32 v58, v62
	v_permlane32_swap_b32_e32 v59, v63
	v_permlane32_swap_b32_e32 v32, v36
	v_permlane32_swap_b32_e32 v33, v37
	v_permlane32_swap_b32_e32 v34, v38
	v_permlane32_swap_b32_e32 v35, v39
	v_permlane32_swap_b32_e32 v40, v44
	v_permlane32_swap_b32_e32 v41, v45
	v_permlane32_swap_b32_e32 v42, v46
	v_permlane32_swap_b32_e32 v43, v47
	v_permlane32_swap_b32_e32 v16, v20
	v_permlane32_swap_b32_e32 v17, v21
	v_permlane32_swap_b32_e32 v18, v22
	v_permlane32_swap_b32_e32 v19, v23
	v_permlane32_swap_b32_e32 v24, v28
	v_permlane32_swap_b32_e32 v25, v29
	v_permlane32_swap_b32_e32 v26, v30
	v_permlane32_swap_b32_e32 v27, v31
	v_permlane32_swap_b32_e32 v0, v4
	v_permlane32_swap_b32_e32 v1, v5
	v_permlane32_swap_b32_e32 v2, v6
	v_permlane32_swap_b32_e32 v3, v7
	v_permlane32_swap_b32_e32 v8, v12
	v_permlane32_swap_b32_e32 v9, v13
	v_permlane32_swap_b32_e32 v10, v14
	v_permlane32_swap_b32_e32 v11, v15
	s_nop 1

.Lg162_loop:
	s_add_u32 s51, s50, 0x10000
	s_sub_u32 s53, s51, 0x28000
	s_cmp_ge_u32 s51, 0x28000
	s_cselect_b32 s51, s53, s51
	s_add_u32 s52, s49, 0x20000
	s_sub_u32 s53, s52, 0x28000
	s_cmp_ge_u32 s52, 0x28000
	s_cselect_b32 s52, s53, s52
	v_add_u32_e32 v167, s50, v145
	s_waitcnt lgkmcnt(4)
	s_waitcnt lgkmcnt(3)
	v_mfma_f32_16x16x32_bf16 v[112:115], v[188:191], v[220:223], v[112:115]
	v_mfma_f32_16x16x32_bf16 v[120:123], v[192:195], v[220:223], v[120:123]
	v_mfma_f32_16x16x32_bf16 v[96:99], v[196:199], v[220:223], v[96:99]
	v_mfma_f32_16x16x32_bf16 v[104:107], v[200:203], v[220:223], v[104:107]
	s_add_u32 m0, s51, s48
	s_nop 0
	global_load_lds_dwordx4 v169, s[64:65]
	s_add_u32 s64, s64, 0x80
	s_addc_u32 s65, s65, 0
	ds_read_b128 v[220:223], v166 offset:8192
	ds_read_b128 v[204:207], v167
	s_waitcnt lgkmcnt(4)
	v_mfma_f32_16x16x32_bf16 v[116:119], v[188:191], v[224:227], v[116:119]
	v_mfma_f32_16x16x32_bf16 v[124:127], v[192:195], v[224:227], v[124:127]
	v_mfma_f32_16x16x32_bf16 v[100:103], v[196:199], v[224:227], v[100:103]
	v_mfma_f32_16x16x32_bf16 v[108:111], v[200:203], v[224:227], v[108:111]
	s_add_u32 s53, s51, s48
	s_add_u32 m0, s53, 0x2000
	s_nop 0
	global_load_lds_dwordx4 v169, s[66:67]
	s_add_u32 s66, s66, 0x80
	s_addc_u32 s67, s67, 0
	ds_read_b128 v[224:227], v166 offset:10240
	ds_read_b128 v[208:211], v167 offset:2048
	s_waitcnt lgkmcnt(5)
	v_mfma_f32_16x16x32_bf16 v[80:83], v[188:191], v[228:231], v[80:83]
	v_mfma_f32_16x16x32_bf16 v[88:91], v[192:195], v[228:231], v[88:91]
	v_mfma_f32_16x16x32_bf16 v[64:67], v[196:199], v[228:231], v[64:67]
	v_mfma_f32_16x16x32_bf16 v[72:75], v[200:203], v[228:231], v[72:75]
	s_add_u32 s53, s51, s48
	s_add_u32 m0, s53, 0x4000
	s_nop 0
	global_load_lds_dwordx4 v169, s[68:69]
	s_add_u32 s68, s68, 0x80
	s_addc_u32 s69, s69, 0
	ds_read_b128 v[228:231], v166 offset:12288
	ds_read_b128 v[212:215], v167 offset:4096
	s_waitcnt lgkmcnt(6)
	v_mfma_f32_16x16x32_bf16 v[84:87], v[188:191], v[232:235], v[84:87]
	v_mfma_f32_16x16x32_bf16 v[92:95], v[192:195], v[232:235], v[92:95]
	v_mfma_f32_16x16x32_bf16 v[68:71], v[196:199], v[232:235], v[68:71]
	v_mfma_f32_16x16x32_bf16 v[76:79], v[200:203], v[232:235], v[76:79]
	s_add_u32 s53, s51, s48
	s_add_u32 m0, s53, 0x6000
	s_nop 0
	global_load_lds_dwordx4 v169, s[70:71]
	s_add_u32 s70, s70, 0x80
	s_addc_u32 s71, s71, 0
	ds_read_b128 v[232:235], v166 offset:14336
	ds_read_b128 v[216:219], v167 offset:6144
	v_add_u32_e32 v166, s49, v143
	s_waitcnt lgkmcnt(7)
	v_mfma_f32_16x16x32_bf16 v[48:51], v[188:191], v[220:223], v[48:51]
	v_mfma_f32_16x16x32_bf16 v[56:59], v[192:195], v[220:223], v[56:59]
	v_mfma_f32_16x16x32_bf16 v[32:35], v[196:199], v[220:223], v[32:35]
	v_mfma_f32_16x16x32_bf16 v[40:43], v[200:203], v[220:223], v[40:43]
	s_add_u32 m0, s52, s48
	s_nop 0
	global_load_lds_dwordx4 v168, s[56:57]
	s_add_u32 s56, s56, 0x80
	s_addc_u32 s57, s57, 0
	ds_read_b128 v[220:223], v166
	s_waitcnt lgkmcnt(6)
	v_mfma_f32_16x16x32_bf16 v[52:55], v[188:191], v[224:227], v[52:55]
	v_mfma_f32_16x16x32_bf16 v[60:63], v[192:195], v[224:227], v[60:63]
	v_mfma_f32_16x16x32_bf16 v[36:39], v[196:199], v[224:227], v[36:39]
	v_mfma_f32_16x16x32_bf16 v[44:47], v[200:203], v[224:227], v[44:47]
	s_add_u32 s53, s52, s48
	s_add_u32 m0, s53, 0x2000
	s_nop 0
	global_load_lds_dwordx4 v168, s[58:59]
	s_add_u32 s58, s58, 0x80
	s_addc_u32 s59, s59, 0
	ds_read_b128 v[224:227], v166 offset:2048
	s_waitcnt lgkmcnt(5)
	v_mfma_f32_16x16x32_bf16 v[16:19], v[188:191], v[228:231], v[16:19]
	v_mfma_f32_16x16x32_bf16 v[24:27], v[192:195], v[228:231], v[24:27]
	v_mfma_f32_16x16x32_bf16 v[0:3], v[196:199], v[228:231], v[0:3]
	v_mfma_f32_16x16x32_bf16 v[8:11], v[200:203], v[228:231], v[8:11]
	s_add_u32 s53, s52, s48
	s_add_u32 m0, s53, 0x4000
	s_nop 0
	global_load_lds_dwordx4 v168, s[60:61]
	s_add_u32 s60, s60, 0x80
	s_addc_u32 s61, s61, 0
	ds_read_b128 v[228:231], v166 offset:4096
	s_waitcnt lgkmcnt(4)
	v_mfma_f32_16x16x32_bf16 v[20:23], v[188:191], v[232:235], v[20:23]
	v_mfma_f32_16x16x32_bf16 v[28:31], v[192:195], v[232:235], v[28:31]
	v_mfma_f32_16x16x32_bf16 v[4:7], v[196:199], v[232:235], v[4:7]
	v_mfma_f32_16x16x32_bf16 v[12:15], v[200:203], v[232:235], v[12:15]
	s_add_u32 s53, s52, s48
	s_add_u32 m0, s53, 0x6000
	s_nop 0
	global_load_lds_dwordx4 v168, s[62:63]
	s_add_u32 s62, s62, 0x80
	s_addc_u32 s63, s63, 0
	ds_read_b128 v[232:235], v166 offset:6144
	s_waitcnt lgkmcnt(4)
	s_waitcnt lgkmcnt(3)
	v_mfma_f32_16x16x32_bf16 v[112:115], v[204:207], v[220:223], v[112:115]
	v_mfma_f32_16x16x32_bf16 v[120:123], v[208:211], v[220:223], v[120:123]
	v_mfma_f32_16x16x32_bf16 v[96:99], v[212:215], v[220:223], v[96:99]
	v_mfma_f32_16x16x32_bf16 v[104:107], v[216:219], v[220:223], v[104:107]
	ds_read_b128 v[220:223], v166 offset:8192
	s_waitcnt lgkmcnt(3)
	v_mfma_f32_16x16x32_bf16 v[116:119], v[204:207], v[224:227], v[116:119]
	v_mfma_f32_16x16x32_bf16 v[124:127], v[208:211], v[224:227], v[124:127]
	v_mfma_f32_16x16x32_bf16 v[100:103], v[212:215], v[224:227], v[100:103]
	v_mfma_f32_16x16x32_bf16 v[108:111], v[216:219], v[224:227], v[108:111]
	ds_read_b128 v[224:227], v166 offset:10240
	s_waitcnt lgkmcnt(3)
	v_mfma_f32_16x16x32_bf16 v[80:83], v[204:207], v[228:231], v[80:83]
	v_mfma_f32_16x16x32_bf16 v[88:91], v[208:211], v[228:231], v[88:91]
	v_mfma_f32_16x16x32_bf16 v[64:67], v[212:215], v[228:231], v[64:67]
	v_mfma_f32_16x16x32_bf16 v[72:75], v[216:219], v[228:231], v[72:75]
	ds_read_b128 v[228:231], v166 offset:12288
	s_waitcnt lgkmcnt(3)
	v_mfma_f32_16x16x32_bf16 v[84:87], v[204:207], v[232:235], v[84:87]
	v_mfma_f32_16x16x32_bf16 v[92:95], v[208:211], v[232:235], v[92:95]
	v_mfma_f32_16x16x32_bf16 v[68:71], v[212:215], v[232:235], v[68:71]
	v_mfma_f32_16x16x32_bf16 v[76:79], v[216:219], v[232:235], v[76:79]
	ds_read_b128 v[232:235], v166 offset:14336
	s_waitcnt lgkmcnt(3)
	v_mfma_f32_16x16x32_bf16 v[48:51], v[204:207], v[220:223], v[48:51]
	v_mfma_f32_16x16x32_bf16 v[56:59], v[208:211], v[220:223], v[56:59]
	v_mfma_f32_16x16x32_bf16 v[32:35], v[212:215], v[220:223], v[32:35]
	v_mfma_f32_16x16x32_bf16 v[40:43], v[216:219], v[220:223], v[40:43]
	s_waitcnt lgkmcnt(2)
	v_mfma_f32_16x16x32_bf16 v[52:55], v[204:207], v[224:227], v[52:55]
	v_mfma_f32_16x16x32_bf16 v[60:63], v[208:211], v[224:227], v[60:63]
	v_mfma_f32_16x16x32_bf16 v[36:39], v[212:215], v[224:227], v[36:39]
	v_mfma_f32_16x16x32_bf16 v[44:47], v[216:219], v[224:227], v[44:47]
	s_waitcnt lgkmcnt(0)
	s_add_u32 s28, s28, 0x80
	s_addc_u32 s29, s29, 0
	s_add_u32 s49, s49, 0x10000
	s_sub_u32 s53, s49, 0x28000
	s_cmp_ge_u32 s49, 0x28000
	s_cselect_b32 s49, s53, s49
	s_mov_b32 s50, s51
	s_waitcnt vmcnt(4)
	s_barrier
	s_barrier
	v_add_u32_e32 v167, s50, v144
	v_add_u32_e32 v166, s49, v142
	ds_read_b128 v[188:191], v167
	ds_read_b128 v[192:195], v167 offset:2048
	ds_read_b128 v[196:199], v167 offset:4096
	ds_read_b128 v[200:203], v167 offset:6144
	ds_read_b128 v[220:223], v166
	ds_read_b128 v[224:227], v166 offset:2048
	v_mfma_f32_16x16x32_bf16 v[16:19], v[204:207], v[228:231], v[16:19]
	v_mfma_f32_16x16x32_bf16 v[24:27], v[208:211], v[228:231], v[24:27]
	v_mfma_f32_16x16x32_bf16 v[0:3], v[212:215], v[228:231], v[0:3]
	v_mfma_f32_16x16x32_bf16 v[8:11], v[216:219], v[228:231], v[8:11]
	ds_read_b128 v[228:231], v166 offset:4096
	v_mfma_f32_16x16x32_bf16 v[20:23], v[204:207], v[232:235], v[20:23]
	v_mfma_f32_16x16x32_bf16 v[28:31], v[208:211], v[232:235], v[28:31]
	v_mfma_f32_16x16x32_bf16 v[4:7], v[212:215], v[232:235], v[4:7]
	v_mfma_f32_16x16x32_bf16 v[12:15], v[216:219], v[232:235], v[12:15]
	ds_read_b128 v[232:235], v166 offset:6144
	s_cmpk_lg_i32 s28, 0xf00
	s_cbranch_scc1 .Lg162_loop
	s_add_u32 s51, s50, 0x10000
	s_sub_u32 s53, s51, 0x28000
	s_cmp_ge_u32 s51, 0x28000
	s_cselect_b32 s51, s53, s51
	v_add_u32_e32 v167, s50, v145
	s_waitcnt lgkmcnt(4)
	s_waitcnt lgkmcnt(3)
	v_mfma_f32_16x16x32_bf16 v[112:115], v[188:191], v[220:223], v[112:115]
	v_mfma_f32_16x16x32_bf16 v[120:123], v[192:195], v[220:223], v[120:123]
	v_mfma_f32_16x16x32_bf16 v[96:99], v[196:199], v[220:223], v[96:99]
	v_mfma_f32_16x16x32_bf16 v[104:107], v[200:203], v[220:223], v[104:107]
	s_add_u32 m0, s51, s48
	s_nop 0
	global_load_lds_dwordx4 v169, s[64:65]
	s_add_u32 s64, s64, 0x80
	s_addc_u32 s65, s65, 0
	ds_read_b128 v[220:223], v166 offset:8192
	ds_read_b128 v[204:207], v167
	s_waitcnt lgkmcnt(4)
	v_mfma_f32_16x16x32_bf16 v[116:119], v[188:191], v[224:227], v[116:119]
	v_mfma_f32_16x16x32_bf16 v[124:127], v[192:195], v[224:227], v[124:127]
	v_mfma_f32_16x16x32_bf16 v[100:103], v[196:199], v[224:227], v[100:103]
	v_mfma_f32_16x16x32_bf16 v[108:111], v[200:203], v[224:227], v[108:111]
	s_add_u32 s53, s51, s48
	s_add_u32 m0, s53, 0x2000
	s_nop 0
	global_load_lds_dwordx4 v169, s[66:67]
	s_add_u32 s66, s66, 0x80
	s_addc_u32 s67, s67, 0
	ds_read_b128 v[224:227], v166 offset:10240
	ds_read_b128 v[208:211], v167 offset:2048
	s_waitcnt lgkmcnt(5)
	v_mfma_f32_16x16x32_bf16 v[80:83], v[188:191], v[228:231], v[80:83]
	v_mfma_f32_16x16x32_bf16 v[88:91], v[192:195], v[228:231], v[88:91]
	v_mfma_f32_16x16x32_bf16 v[64:67], v[196:199], v[228:231], v[64:67]
	v_mfma_f32_16x16x32_bf16 v[72:75], v[200:203], v[228:231], v[72:75]
	s_add_u32 s53, s51, s48
	s_add_u32 m0, s53, 0x4000
	s_nop 0
	global_load_lds_dwordx4 v169, s[68:69]
	s_add_u32 s68, s68, 0x80
	s_addc_u32 s69, s69, 0
	ds_read_b128 v[228:231], v166 offset:12288
	ds_read_b128 v[212:215], v167 offset:4096
	s_waitcnt lgkmcnt(6)
	v_mfma_f32_16x16x32_bf16 v[84:87], v[188:191], v[232:235], v[84:87]
	v_mfma_f32_16x16x32_bf16 v[92:95], v[192:195], v[232:235], v[92:95]
	v_mfma_f32_16x16x32_bf16 v[68:71], v[196:199], v[232:235], v[68:71]
	v_mfma_f32_16x16x32_bf16 v[76:79], v[200:203], v[232:235], v[76:79]
	s_add_u32 s53, s51, s48
	s_add_u32 m0, s53, 0x6000
	s_nop 0
	global_load_lds_dwordx4 v169, s[70:71]
	s_add_u32 s70, s70, 0x80
	s_addc_u32 s71, s71, 0
	ds_read_b128 v[232:235], v166 offset:14336
	ds_read_b128 v[216:219], v167 offset:6144
	v_add_u32_e32 v166, s49, v143
	s_waitcnt lgkmcnt(7)
	v_mfma_f32_16x16x32_bf16 v[48:51], v[188:191], v[220:223], v[48:51]
	v_mfma_f32_16x16x32_bf16 v[56:59], v[192:195], v[220:223], v[56:59]
	v_mfma_f32_16x16x32_bf16 v[32:35], v[196:199], v[220:223], v[32:35]
	v_mfma_f32_16x16x32_bf16 v[40:43], v[200:203], v[220:223], v[40:43]
	ds_read_b128 v[220:223], v166
	s_waitcnt lgkmcnt(6)
	v_mfma_f32_16x16x32_bf16 v[52:55], v[188:191], v[224:227], v[52:55]
	v_mfma_f32_16x16x32_bf16 v[60:63], v[192:195], v[224:227], v[60:63]
	v_mfma_f32_16x16x32_bf16 v[36:39], v[196:199], v[224:227], v[36:39]
	v_mfma_f32_16x16x32_bf16 v[44:47], v[200:203], v[224:227], v[44:47]
	ds_read_b128 v[224:227], v166 offset:2048
	s_waitcnt lgkmcnt(5)
	v_mfma_f32_16x16x32_bf16 v[16:19], v[188:191], v[228:231], v[16:19]
	v_mfma_f32_16x16x32_bf16 v[24:27], v[192:195], v[228:231], v[24:27]
	v_mfma_f32_16x16x32_bf16 v[0:3], v[196:199], v[228:231], v[0:3]
	v_mfma_f32_16x16x32_bf16 v[8:11], v[200:203], v[228:231], v[8:11]
	ds_read_b128 v[228:231], v166 offset:4096
	s_waitcnt lgkmcnt(4)
	v_mfma_f32_16x16x32_bf16 v[20:23], v[188:191], v[232:235], v[20:23]
	v_mfma_f32_16x16x32_bf16 v[28:31], v[192:195], v[232:235], v[28:31]
	v_mfma_f32_16x16x32_bf16 v[4:7], v[196:199], v[232:235], v[4:7]
	v_mfma_f32_16x16x32_bf16 v[12:15], v[200:203], v[232:235], v[12:15]
	ds_read_b128 v[232:235], v166 offset:6144
	s_waitcnt lgkmcnt(4)
	s_waitcnt lgkmcnt(3)
	v_mfma_f32_16x16x32_bf16 v[112:115], v[204:207], v[220:223], v[112:115]
	v_mfma_f32_16x16x32_bf16 v[120:123], v[208:211], v[220:223], v[120:123]
	v_mfma_f32_16x16x32_bf16 v[96:99], v[212:215], v[220:223], v[96:99]
	v_mfma_f32_16x16x32_bf16 v[104:107], v[216:219], v[220:223], v[104:107]
	ds_read_b128 v[220:223], v166 offset:8192
	s_waitcnt lgkmcnt(3)
	v_mfma_f32_16x16x32_bf16 v[116:119], v[204:207], v[224:227], v[116:119]
	v_mfma_f32_16x16x32_bf16 v[124:127], v[208:211], v[224:227], v[124:127]
	v_mfma_f32_16x16x32_bf16 v[100:103], v[212:215], v[224:227], v[100:103]
	v_mfma_f32_16x16x32_bf16 v[108:111], v[216:219], v[224:227], v[108:111]
	ds_read_b128 v[224:227], v166 offset:10240
	s_waitcnt lgkmcnt(3)
	v_mfma_f32_16x16x32_bf16 v[80:83], v[204:207], v[228:231], v[80:83]
	v_mfma_f32_16x16x32_bf16 v[88:91], v[208:211], v[228:231], v[88:91]
	v_mfma_f32_16x16x32_bf16 v[64:67], v[212:215], v[228:231], v[64:67]
	v_mfma_f32_16x16x32_bf16 v[72:75], v[216:219], v[228:231], v[72:75]
	ds_read_b128 v[228:231], v166 offset:12288
	s_waitcnt lgkmcnt(3)
	v_mfma_f32_16x16x32_bf16 v[84:87], v[204:207], v[232:235], v[84:87]
	v_mfma_f32_16x16x32_bf16 v[92:95], v[208:211], v[232:235], v[92:95]
	v_mfma_f32_16x16x32_bf16 v[68:71], v[212:215], v[232:235], v[68:71]
	v_mfma_f32_16x16x32_bf16 v[76:79], v[216:219], v[232:235], v[76:79]
	ds_read_b128 v[232:235], v166 offset:14336
	s_waitcnt lgkmcnt(3)
	v_mfma_f32_16x16x32_bf16 v[48:51], v[204:207], v[220:223], v[48:51]
	v_mfma_f32_16x16x32_bf16 v[56:59], v[208:211], v[220:223], v[56:59]
	v_mfma_f32_16x16x32_bf16 v[32:35], v[212:215], v[220:223], v[32:35]
	v_mfma_f32_16x16x32_bf16 v[40:43], v[216:219], v[220:223], v[40:43]
	s_waitcnt lgkmcnt(2)
	v_mfma_f32_16x16x32_bf16 v[52:55], v[204:207], v[224:227], v[52:55]
	v_mfma_f32_16x16x32_bf16 v[60:63], v[208:211], v[224:227], v[60:63]
	v_mfma_f32_16x16x32_bf16 v[36:39], v[212:215], v[224:227], v[36:39]
	v_mfma_f32_16x16x32_bf16 v[44:47], v[216:219], v[224:227], v[44:47]
	s_waitcnt lgkmcnt(0)
	s_add_u32 s28, s28, 0x80
	s_addc_u32 s29, s29, 0
	s_add_u32 s49, s49, 0x10000
	s_sub_u32 s53, s49, 0x28000
	s_cmp_ge_u32 s49, 0x28000
	s_cselect_b32 s49, s53, s49
	s_mov_b32 s50, s51
	s_waitcnt vmcnt(0)
	s_barrier
	s_barrier
	v_add_u32_e32 v167, s50, v144
	v_add_u32_e32 v166, s49, v142
	ds_read_b128 v[188:191], v167
	ds_read_b128 v[192:195], v167 offset:2048
	ds_read_b128 v[196:199], v167 offset:4096
	ds_read_b128 v[200:203], v167 offset:6144
	ds_read_b128 v[220:223], v166
	ds_read_b128 v[224:227], v166 offset:2048
	v_mfma_f32_16x16x32_bf16 v[16:19], v[204:207], v[228:231], v[16:19]
	v_mfma_f32_16x16x32_bf16 v[24:27], v[208:211], v[228:231], v[24:27]
	v_mfma_f32_16x16x32_bf16 v[0:3], v[212:215], v[228:231], v[0:3]
	v_mfma_f32_16x16x32_bf16 v[8:11], v[216:219], v[228:231], v[8:11]
	ds_read_b128 v[228:231], v166 offset:4096
	v_mfma_f32_16x16x32_bf16 v[20:23], v[204:207], v[232:235], v[20:23]
	v_mfma_f32_16x16x32_bf16 v[28:31], v[208:211], v[232:235], v[28:31]
	v_mfma_f32_16x16x32_bf16 v[4:7], v[212:215], v[232:235], v[4:7]
	v_mfma_f32_16x16x32_bf16 v[12:15], v[216:219], v[232:235], v[12:15]
	ds_read_b128 v[232:235], v166 offset:6144
	v_add_u32_e32 v167, s50, v145
	s_waitcnt lgkmcnt(4)
	s_waitcnt lgkmcnt(3)
	v_mfma_f32_16x16x32_bf16 v[112:115], v[188:191], v[220:223], v[112:115]
	v_mfma_f32_16x16x32_bf16 v[120:123], v[192:195], v[220:223], v[120:123]
	v_mfma_f32_16x16x32_bf16 v[96:99], v[196:199], v[220:223], v[96:99]
	v_mfma_f32_16x16x32_bf16 v[104:107], v[200:203], v[220:223], v[104:107]
	ds_read_b128 v[220:223], v166 offset:8192
	ds_read_b128 v[204:207], v167
	s_waitcnt lgkmcnt(4)
	v_mfma_f32_16x16x32_bf16 v[116:119], v[188:191], v[224:227], v[116:119]
	v_mfma_f32_16x16x32_bf16 v[124:127], v[192:195], v[224:227], v[124:127]
	v_mfma_f32_16x16x32_bf16 v[100:103], v[196:199], v[224:227], v[100:103]
	v_mfma_f32_16x16x32_bf16 v[108:111], v[200:203], v[224:227], v[108:111]
	ds_read_b128 v[224:227], v166 offset:10240
	ds_read_b128 v[208:211], v167 offset:2048
	s_waitcnt lgkmcnt(5)
	v_mfma_f32_16x16x32_bf16 v[80:83], v[188:191], v[228:231], v[80:83]
	v_mfma_f32_16x16x32_bf16 v[88:91], v[192:195], v[228:231], v[88:91]
	v_mfma_f32_16x16x32_bf16 v[64:67], v[196:199], v[228:231], v[64:67]
	v_mfma_f32_16x16x32_bf16 v[72:75], v[200:203], v[228:231], v[72:75]
	ds_read_b128 v[228:231], v166 offset:12288
	ds_read_b128 v[212:215], v167 offset:4096
	s_waitcnt lgkmcnt(6)
	v_mfma_f32_16x16x32_bf16 v[84:87], v[188:191], v[232:235], v[84:87]
	v_mfma_f32_16x16x32_bf16 v[92:95], v[192:195], v[232:235], v[92:95]
	v_mfma_f32_16x16x32_bf16 v[68:71], v[196:199], v[232:235], v[68:71]
	v_mfma_f32_16x16x32_bf16 v[76:79], v[200:203], v[232:235], v[76:79]
	ds_read_b128 v[232:235], v166 offset:14336
	ds_read_b128 v[216:219], v167 offset:6144
	v_add_u32_e32 v166, s49, v143
	s_waitcnt lgkmcnt(7)
	v_mfma_f32_16x16x32_bf16 v[48:51], v[188:191], v[220:223], v[48:51]
	v_mfma_f32_16x16x32_bf16 v[56:59], v[192:195], v[220:223], v[56:59]
	v_mfma_f32_16x16x32_bf16 v[32:35], v[196:199], v[220:223], v[32:35]
	v_mfma_f32_16x16x32_bf16 v[40:43], v[200:203], v[220:223], v[40:43]
	ds_read_b128 v[220:223], v166
	s_waitcnt lgkmcnt(6)
	v_mfma_f32_16x16x32_bf16 v[52:55], v[188:191], v[224:227], v[52:55]
	v_mfma_f32_16x16x32_bf16 v[60:63], v[192:195], v[224:227], v[60:63]
	v_mfma_f32_16x16x32_bf16 v[36:39], v[196:199], v[224:227], v[36:39]
	v_mfma_f32_16x16x32_bf16 v[44:47], v[200:203], v[224:227], v[44:47]
	ds_read_b128 v[224:227], v166 offset:2048
	s_waitcnt lgkmcnt(5)
	v_mfma_f32_16x16x32_bf16 v[16:19], v[188:191], v[228:231], v[16:19]
	v_mfma_f32_16x16x32_bf16 v[24:27], v[192:195], v[228:231], v[24:27]
	v_mfma_f32_16x16x32_bf16 v[0:3], v[196:199], v[228:231], v[0:3]
	v_mfma_f32_16x16x32_bf16 v[8:11], v[200:203], v[228:231], v[8:11]
	ds_read_b128 v[228:231], v166 offset:4096
	s_waitcnt lgkmcnt(4)
	v_mfma_f32_16x16x32_bf16 v[20:23], v[188:191], v[232:235], v[20:23]
	v_mfma_f32_16x16x32_bf16 v[28:31], v[192:195], v[232:235], v[28:31]
	v_mfma_f32_16x16x32_bf16 v[4:7], v[196:199], v[232:235], v[4:7]
	v_mfma_f32_16x16x32_bf16 v[12:15], v[200:203], v[232:235], v[12:15]
	ds_read_b128 v[232:235], v166 offset:6144
	s_waitcnt lgkmcnt(4)
	s_waitcnt lgkmcnt(3)
	v_mfma_f32_16x16x32_bf16 v[112:115], v[204:207], v[220:223], v[112:115]
	v_mfma_f32_16x16x32_bf16 v[120:123], v[208:211], v[220:223], v[120:123]
	v_mfma_f32_16x16x32_bf16 v[96:99], v[212:215], v[220:223], v[96:99]
	v_mfma_f32_16x16x32_bf16 v[104:107], v[216:219], v[220:223], v[104:107]
	ds_read_b128 v[220:223], v166 offset:8192
	s_waitcnt lgkmcnt(3)
	v_mfma_f32_16x16x32_bf16 v[116:119], v[204:207], v[224:227], v[116:119]
	v_mfma_f32_16x16x32_bf16 v[124:127], v[208:211], v[224:227], v[124:127]
	v_mfma_f32_16x16x32_bf16 v[100:103], v[212:215], v[224:227], v[100:103]
	v_mfma_f32_16x16x32_bf16 v[108:111], v[216:219], v[224:227], v[108:111]
	ds_read_b128 v[224:227], v166 offset:10240
	s_waitcnt lgkmcnt(3)
	v_mfma_f32_16x16x32_bf16 v[80:83], v[204:207], v[228:231], v[80:83]
	v_mfma_f32_16x16x32_bf16 v[88:91], v[208:211], v[228:231], v[88:91]
	v_mfma_f32_16x16x32_bf16 v[64:67], v[212:215], v[228:231], v[64:67]
	v_mfma_f32_16x16x32_bf16 v[72:75], v[216:219], v[228:231], v[72:75]
	ds_read_b128 v[228:231], v166 offset:12288
	s_waitcnt lgkmcnt(3)
	v_mfma_f32_16x16x32_bf16 v[84:87], v[204:207], v[232:235], v[84:87]
	v_mfma_f32_16x16x32_bf16 v[92:95], v[208:211], v[232:235], v[92:95]
	v_mfma_f32_16x16x32_bf16 v[68:71], v[212:215], v[232:235], v[68:71]
	v_mfma_f32_16x16x32_bf16 v[76:79], v[216:219], v[232:235], v[76:79]
	ds_read_b128 v[232:235], v166 offset:14336
	s_waitcnt lgkmcnt(3)
	v_mfma_f32_16x16x32_bf16 v[48:51], v[204:207], v[220:223], v[48:51]
	v_mfma_f32_16x16x32_bf16 v[56:59], v[208:211], v[220:223], v[56:59]
	v_mfma_f32_16x16x32_bf16 v[32:35], v[212:215], v[220:223], v[32:35]
	v_mfma_f32_16x16x32_bf16 v[40:43], v[216:219], v[220:223], v[40:43]
	s_waitcnt lgkmcnt(2)
	v_mfma_f32_16x16x32_bf16 v[52:55], v[204:207], v[224:227], v[52:55]
	v_mfma_f32_16x16x32_bf16 v[60:63], v[208:211], v[224:227], v[60:63]
	v_mfma_f32_16x16x32_bf16 v[36:39], v[212:215], v[224:227], v[36:39]
	v_mfma_f32_16x16x32_bf16 v[44:47], v[216:219], v[224:227], v[44:47]
	s_waitcnt lgkmcnt(0)
	s_waitcnt vmcnt(0)
	s_barrier
	s_barrier
	v_mfma_f32_16x16x32_bf16 v[16:19], v[204:207], v[228:231], v[16:19]
	v_mfma_f32_16x16x32_bf16 v[24:27], v[208:211], v[228:231], v[24:27]
	v_mfma_f32_16x16x32_bf16 v[0:3], v[212:215], v[228:231], v[0:3]
	v_mfma_f32_16x16x32_bf16 v[8:11], v[216:219], v[228:231], v[8:11]
	v_mfma_f32_16x16x32_bf16 v[20:23], v[204:207], v[232:235], v[20:23]
	v_mfma_f32_16x16x32_bf16 v[28:31], v[208:211], v[232:235], v[28:31]
	v_mfma_f32_16x16x32_bf16 v[4:7], v[212:215], v[232:235], v[4:7]
	v_mfma_f32_16x16x32_bf16 v[12:15], v[216:219], v[232:235], v[12:15]
	s_nop 15
	v_permlane16_swap_b32_e32 v112, v116
	v_permlane16_swap_b32_e32 v113, v117
	v_permlane16_swap_b32_e32 v114, v118
	v_permlane16_swap_b32_e32 v115, v119
	v_permlane16_swap_b32_e32 v120, v124
	v_permlane16_swap_b32_e32 v121, v125
	v_permlane16_swap_b32_e32 v122, v126
	v_permlane16_swap_b32_e32 v123, v127
	v_permlane16_swap_b32_e32 v96, v100
	v_permlane16_swap_b32_e32 v97, v101
	v_permlane16_swap_b32_e32 v98, v102
	v_permlane16_swap_b32_e32 v99, v103
	v_permlane16_swap_b32_e32 v104, v108
	v_permlane16_swap_b32_e32 v105, v109
	v_permlane16_swap_b32_e32 v106, v110
	v_permlane16_swap_b32_e32 v107, v111
	v_permlane16_swap_b32_e32 v80, v84
	v_permlane16_swap_b32_e32 v81, v85
	v_permlane16_swap_b32_e32 v82, v86
	v_permlane16_swap_b32_e32 v83, v87
	v_permlane16_swap_b32_e32 v88, v92
	v_permlane16_swap_b32_e32 v89, v93
	v_permlane16_swap_b32_e32 v90, v94
	v_permlane16_swap_b32_e32 v91, v95
	v_permlane16_swap_b32_e32 v64, v68
	v_permlane16_swap_b32_e32 v65, v69
	v_permlane16_swap_b32_e32 v66, v70
	v_permlane16_swap_b32_e32 v67, v71
	v_permlane16_swap_b32_e32 v72, v76
	v_permlane16_swap_b32_e32 v73, v77
	v_permlane16_swap_b32_e32 v74, v78
	v_permlane16_swap_b32_e32 v75, v79
	v_permlane16_swap_b32_e32 v48, v52
	v_permlane16_swap_b32_e32 v49, v53
	v_permlane16_swap_b32_e32 v50, v54
	v_permlane16_swap_b32_e32 v51, v55
	v_permlane16_swap_b32_e32 v56, v60
	v_permlane16_swap_b32_e32 v57, v61
	v_permlane16_swap_b32_e32 v58, v62
	v_permlane16_swap_b32_e32 v59, v63
	v_permlane16_swap_b32_e32 v32, v36
	v_permlane16_swap_b32_e32 v33, v37
	v_permlane16_swap_b32_e32 v34, v38
	v_permlane16_swap_b32_e32 v35, v39
	v_permlane16_swap_b32_e32 v40, v44
	v_permlane16_swap_b32_e32 v41, v45
	v_permlane16_swap_b32_e32 v42, v46
	v_permlane16_swap_b32_e32 v43, v47
	v_permlane16_swap_b32_e32 v16, v20
	v_permlane16_swap_b32_e32 v17, v21
	v_permlane16_swap_b32_e32 v18, v22
	v_permlane16_swap_b32_e32 v19, v23
	v_permlane16_swap_b32_e32 v24, v28
	v_permlane16_swap_b32_e32 v25, v29
	v_permlane16_swap_b32_e32 v26, v30
	v_permlane16_swap_b32_e32 v27, v31
	v_permlane16_swap_b32_e32 v0, v4
	v_permlane16_swap_b32_e32 v1, v5
	v_permlane16_swap_b32_e32 v2, v6
	v_permlane16_swap_b32_e32 v3, v7
	v_permlane16_swap_b32_e32 v8, v12
	v_permlane16_swap_b32_e32 v9, v13
	v_permlane16_swap_b32_e32 v10, v14
	v_permlane16_swap_b32_e32 v11, v15
	v_permlane32_swap_b32_e32 v112, v116
	v_permlane32_swap_b32_e32 v113, v117
	v_permlane32_swap_b32_e32 v114, v118
	v_permlane32_swap_b32_e32 v115, v119
	v_permlane32_swap_b32_e32 v120, v124
	v_permlane32_swap_b32_e32 v121, v125
	v_permlane32_swap_b32_e32 v122, v126
	v_permlane32_swap_b32_e32 v123, v127
	v_permlane32_swap_b32_e32 v96, v100
	v_permlane32_swap_b32_e32 v97, v101
	v_permlane32_swap_b32_e32 v98, v102
	v_permlane32_swap_b32_e32 v99, v103
	v_permlane32_swap_b32_e32 v104, v108
	v_permlane32_swap_b32_e32 v105, v109
	v_permlane32_swap_b32_e32 v106, v110
	v_permlane32_swap_b32_e32 v107, v111
	v_permlane32_swap_b32_e32 v80, v84
	v_permlane32_swap_b32_e32 v81, v85
	v_permlane32_swap_b32_e32 v82, v86
	v_permlane32_swap_b32_e32 v83, v87
	v_permlane32_swap_b32_e32 v88, v92
	v_permlane32_swap_b32_e32 v89, v93
	v_permlane32_swap_b32_e32 v90, v94
	v_permlane32_swap_b32_e32 v91, v95
	v_permlane32_swap_b32_e32 v64, v68
	v_permlane32_swap_b32_e32 v65, v69
	v_permlane32_swap_b32_e32 v66, v70
	v_permlane32_swap_b32_e32 v67, v71
	v_permlane32_swap_b32_e32 v72, v76
	v_permlane32_swap_b32_e32 v73, v77
	v_permlane32_swap_b32_e32 v74, v78
	v_permlane32_swap_b32_e32 v75, v79
	v_permlane32_swap_b32_e32 v48, v52
	v_permlane32_swap_b32_e32 v49, v53
	v_permlane32_swap_b32_e32 v50, v54
	v_permlane32_swap_b32_e32 v51, v55
	v_permlane32_swap_b32_e32 v56, v60
	v_permlane32_swap_b32_e32 v57, v61
	v_permlane32_swap_b32_e32 v58, v62
	v_permlane32_swap_b32_e32 v59, v63
	v_permlane32_swap_b32_e32 v32, v36
	v_permlane32_swap_b32_e32 v33, v37
	v_permlane32_swap_b32_e32 v34, v38
	v_permlane32_swap_b32_e32 v35, v39
	v_permlane32_swap_b32_e32 v40, v44
	v_permlane32_swap_b32_e32 v41, v45
	v_permlane32_swap_b32_e32 v42, v46
	v_permlane32_swap_b32_e32 v43, v47
	v_permlane32_swap_b32_e32 v16, v20
	v_permlane32_swap_b32_e32 v17, v21
	v_permlane32_swap_b32_e32 v18, v22
	v_permlane32_swap_b32_e32 v19, v23
	v_permlane32_swap_b32_e32 v24, v28
	v_permlane32_swap_b32_e32 v25, v29
	v_permlane32_swap_b32_e32 v26, v30
	v_permlane32_swap_b32_e32 v27, v31
	v_permlane32_swap_b32_e32 v0, v4
	v_permlane32_swap_b32_e32 v1, v5
	v_permlane32_swap_b32_e32 v2, v6
	v_permlane32_swap_b32_e32 v3, v7
	v_permlane32_swap_b32_e32 v8, v12
	v_permlane32_swap_b32_e32 v9, v13
	v_permlane32_swap_b32_e32 v10, v14
	v_permlane32_swap_b32_e32 v11, v15
	s_nop 1
	s_branch .LBB0_163

.Lg163_loop:
	s_add_u32 s51, s50, 0x10000
	s_sub_u32 s53, s51, 0x28000
	s_cmp_ge_u32 s51, 0x28000
	s_cselect_b32 s51, s53, s51
	s_add_u32 s52, s49, 0x20000
	s_sub_u32 s53, s52, 0x28000
	s_cmp_ge_u32 s52, 0x28000
	s_cselect_b32 s52, s53, s52
	v_add_u32_e32 v246, s50, v244
	s_waitcnt lgkmcnt(4)
	s_waitcnt lgkmcnt(3)
	v_mfma_f32_16x16x32_bf16 v[112:115], v[192:195], v[224:227], v[112:115]
	v_mfma_f32_16x16x32_bf16 v[120:123], v[196:199], v[224:227], v[120:123]
	v_mfma_f32_16x16x32_bf16 v[96:99], v[200:203], v[224:227], v[96:99]
	v_mfma_f32_16x16x32_bf16 v[104:107], v[204:207], v[224:227], v[104:107]
	s_add_u32 m0, s51, s48
	s_nop 0
	global_load_lds_dwordx4 v248, s[64:65]
	s_add_u32 s64, s64, 0x80
	s_addc_u32 s65, s65, 0
	ds_read_b128 v[224:227], v245 offset:8192
	ds_read_b128 v[208:211], v246
	s_waitcnt lgkmcnt(4)
	v_mfma_f32_16x16x32_bf16 v[116:119], v[192:195], v[228:231], v[116:119]
	v_mfma_f32_16x16x32_bf16 v[124:127], v[196:199], v[228:231], v[124:127]
	v_mfma_f32_16x16x32_bf16 v[100:103], v[200:203], v[228:231], v[100:103]
	v_mfma_f32_16x16x32_bf16 v[108:111], v[204:207], v[228:231], v[108:111]
	s_add_u32 s53, s51, s48
	s_add_u32 m0, s53, 0x2000
	s_nop 0
	global_load_lds_dwordx4 v248, s[66:67]
	s_add_u32 s66, s66, 0x80
	s_addc_u32 s67, s67, 0
	ds_read_b128 v[228:231], v245 offset:10240
	ds_read_b128 v[212:215], v246 offset:2048
	s_waitcnt lgkmcnt(5)
	v_mfma_f32_16x16x32_bf16 v[80:83], v[192:195], v[232:235], v[80:83]
	v_mfma_f32_16x16x32_bf16 v[88:91], v[196:199], v[232:235], v[88:91]
	v_mfma_f32_16x16x32_bf16 v[64:67], v[200:203], v[232:235], v[64:67]
	v_mfma_f32_16x16x32_bf16 v[72:75], v[204:207], v[232:235], v[72:75]
	s_add_u32 s53, s51, s48
	s_add_u32 m0, s53, 0x4000
	s_nop 0
	global_load_lds_dwordx4 v248, s[68:69]
	s_add_u32 s68, s68, 0x80
	s_addc_u32 s69, s69, 0
	ds_read_b128 v[232:235], v245 offset:12288
	ds_read_b128 v[216:219], v246 offset:4096
	s_waitcnt lgkmcnt(6)
	v_mfma_f32_16x16x32_bf16 v[84:87], v[192:195], v[236:239], v[84:87]
	v_mfma_f32_16x16x32_bf16 v[92:95], v[196:199], v[236:239], v[92:95]
	v_mfma_f32_16x16x32_bf16 v[68:71], v[200:203], v[236:239], v[68:71]
	v_mfma_f32_16x16x32_bf16 v[76:79], v[204:207], v[236:239], v[76:79]
	s_add_u32 s53, s51, s48
	s_add_u32 m0, s53, 0x6000
	s_nop 0
	global_load_lds_dwordx4 v248, s[70:71]
	s_add_u32 s70, s70, 0x80
	s_addc_u32 s71, s71, 0
	ds_read_b128 v[236:239], v245 offset:14336
	ds_read_b128 v[220:223], v246 offset:6144
	v_add_u32_e32 v245, s49, v241
	s_waitcnt lgkmcnt(7)
	v_mfma_f32_16x16x32_bf16 v[48:51], v[192:195], v[224:227], v[48:51]
	v_mfma_f32_16x16x32_bf16 v[56:59], v[196:199], v[224:227], v[56:59]
	v_mfma_f32_16x16x32_bf16 v[32:35], v[200:203], v[224:227], v[32:35]
	v_mfma_f32_16x16x32_bf16 v[40:43], v[204:207], v[224:227], v[40:43]
	s_add_u32 m0, s52, s48
	s_nop 0
	global_load_lds_dwordx4 v247, s[56:57]
	s_add_u32 s56, s56, 0x80
	s_addc_u32 s57, s57, 0
	ds_read_b128 v[224:227], v245
	s_waitcnt lgkmcnt(6)
	v_mfma_f32_16x16x32_bf16 v[52:55], v[192:195], v[228:231], v[52:55]
	v_mfma_f32_16x16x32_bf16 v[60:63], v[196:199], v[228:231], v[60:63]
	v_mfma_f32_16x16x32_bf16 v[36:39], v[200:203], v[228:231], v[36:39]
	v_mfma_f32_16x16x32_bf16 v[44:47], v[204:207], v[228:231], v[44:47]
	s_add_u32 s53, s52, s48
	s_add_u32 m0, s53, 0x2000
	s_nop 0
	global_load_lds_dwordx4 v247, s[58:59]
	s_add_u32 s58, s58, 0x80
	s_addc_u32 s59, s59, 0
	ds_read_b128 v[228:231], v245 offset:2048
	s_waitcnt lgkmcnt(5)
	v_mfma_f32_16x16x32_bf16 v[16:19], v[192:195], v[232:235], v[16:19]
	v_mfma_f32_16x16x32_bf16 v[24:27], v[196:199], v[232:235], v[24:27]
	v_mfma_f32_16x16x32_bf16 v[0:3], v[200:203], v[232:235], v[0:3]
	v_mfma_f32_16x16x32_bf16 v[8:11], v[204:207], v[232:235], v[8:11]
	s_add_u32 s53, s52, s48
	s_add_u32 m0, s53, 0x4000
	s_nop 0
	global_load_lds_dwordx4 v247, s[60:61]
	s_add_u32 s60, s60, 0x80
	s_addc_u32 s61, s61, 0
	ds_read_b128 v[232:235], v245 offset:4096
	s_waitcnt lgkmcnt(4)
	v_mfma_f32_16x16x32_bf16 v[20:23], v[192:195], v[236:239], v[20:23]
	v_mfma_f32_16x16x32_bf16 v[28:31], v[196:199], v[236:239], v[28:31]
	v_mfma_f32_16x16x32_bf16 v[4:7], v[200:203], v[236:239], v[4:7]
	v_mfma_f32_16x16x32_bf16 v[12:15], v[204:207], v[236:239], v[12:15]
	s_add_u32 s53, s52, s48
	s_add_u32 m0, s53, 0x6000
	s_nop 0
	global_load_lds_dwordx4 v247, s[62:63]
	s_add_u32 s62, s62, 0x80
	s_addc_u32 s63, s63, 0
	ds_read_b128 v[236:239], v245 offset:6144
	s_waitcnt lgkmcnt(4)
	s_waitcnt lgkmcnt(3)
	v_mfma_f32_16x16x32_bf16 v[112:115], v[208:211], v[224:227], v[112:115]
	v_mfma_f32_16x16x32_bf16 v[120:123], v[212:215], v[224:227], v[120:123]
	v_mfma_f32_16x16x32_bf16 v[96:99], v[216:219], v[224:227], v[96:99]
	v_mfma_f32_16x16x32_bf16 v[104:107], v[220:223], v[224:227], v[104:107]
	ds_read_b128 v[224:227], v245 offset:8192
	s_waitcnt lgkmcnt(3)
	v_mfma_f32_16x16x32_bf16 v[116:119], v[208:211], v[228:231], v[116:119]
	v_mfma_f32_16x16x32_bf16 v[124:127], v[212:215], v[228:231], v[124:127]
	v_mfma_f32_16x16x32_bf16 v[100:103], v[216:219], v[228:231], v[100:103]
	v_mfma_f32_16x16x32_bf16 v[108:111], v[220:223], v[228:231], v[108:111]
	ds_read_b128 v[228:231], v245 offset:10240
	s_waitcnt lgkmcnt(3)
	v_mfma_f32_16x16x32_bf16 v[80:83], v[208:211], v[232:235], v[80:83]
	v_mfma_f32_16x16x32_bf16 v[88:91], v[212:215], v[232:235], v[88:91]
	v_mfma_f32_16x16x32_bf16 v[64:67], v[216:219], v[232:235], v[64:67]
	v_mfma_f32_16x16x32_bf16 v[72:75], v[220:223], v[232:235], v[72:75]
	ds_read_b128 v[232:235], v245 offset:12288
	s_waitcnt lgkmcnt(3)
	v_mfma_f32_16x16x32_bf16 v[84:87], v[208:211], v[236:239], v[84:87]
	v_mfma_f32_16x16x32_bf16 v[92:95], v[212:215], v[236:239], v[92:95]
	v_mfma_f32_16x16x32_bf16 v[68:71], v[216:219], v[236:239], v[68:71]
	v_mfma_f32_16x16x32_bf16 v[76:79], v[220:223], v[236:239], v[76:79]
	ds_read_b128 v[236:239], v245 offset:14336
	s_waitcnt lgkmcnt(3)
	v_mfma_f32_16x16x32_bf16 v[48:51], v[208:211], v[224:227], v[48:51]
	v_mfma_f32_16x16x32_bf16 v[56:59], v[212:215], v[224:227], v[56:59]
	v_mfma_f32_16x16x32_bf16 v[32:35], v[216:219], v[224:227], v[32:35]
	v_mfma_f32_16x16x32_bf16 v[40:43], v[220:223], v[224:227], v[40:43]
	s_waitcnt lgkmcnt(2)
	v_mfma_f32_16x16x32_bf16 v[52:55], v[208:211], v[228:231], v[52:55]
	v_mfma_f32_16x16x32_bf16 v[60:63], v[212:215], v[228:231], v[60:63]
	v_mfma_f32_16x16x32_bf16 v[36:39], v[216:219], v[228:231], v[36:39]
	v_mfma_f32_16x16x32_bf16 v[44:47], v[220:223], v[228:231], v[44:47]
	s_waitcnt lgkmcnt(0)
	s_add_u32 s28, s28, 0x80
	s_addc_u32 s29, s29, 0
	s_add_u32 s49, s49, 0x10000
	s_sub_u32 s53, s49, 0x28000
	s_cmp_ge_u32 s49, 0x28000
	s_cselect_b32 s49, s53, s49
	s_mov_b32 s50, s51
	s_waitcnt vmcnt(4)
	s_barrier
	s_barrier
	v_add_u32_e32 v246, s50, v243
	v_add_u32_e32 v245, s49, v240
	ds_read_b128 v[192:195], v246
	ds_read_b128 v[196:199], v246 offset:2048
	ds_read_b128 v[200:203], v246 offset:4096
	ds_read_b128 v[204:207], v246 offset:6144
	ds_read_b128 v[224:227], v245
	ds_read_b128 v[228:231], v245 offset:2048
	v_mfma_f32_16x16x32_bf16 v[16:19], v[208:211], v[232:235], v[16:19]
	v_mfma_f32_16x16x32_bf16 v[24:27], v[212:215], v[232:235], v[24:27]
	v_mfma_f32_16x16x32_bf16 v[0:3], v[216:219], v[232:235], v[0:3]
	v_mfma_f32_16x16x32_bf16 v[8:11], v[220:223], v[232:235], v[8:11]
	ds_read_b128 v[232:235], v245 offset:4096
	v_mfma_f32_16x16x32_bf16 v[20:23], v[208:211], v[236:239], v[20:23]
	v_mfma_f32_16x16x32_bf16 v[28:31], v[212:215], v[236:239], v[28:31]
	v_mfma_f32_16x16x32_bf16 v[4:7], v[216:219], v[236:239], v[4:7]
	v_mfma_f32_16x16x32_bf16 v[12:15], v[220:223], v[236:239], v[12:15]
	ds_read_b128 v[236:239], v245 offset:6144
	s_cmpk_lg_i32 s28, 0xf00
	s_cbranch_scc1 .Lg163_loop
	s_add_u32 s51, s50, 0x10000
	s_sub_u32 s53, s51, 0x28000
	s_cmp_ge_u32 s51, 0x28000
	s_cselect_b32 s51, s53, s51
	v_add_u32_e32 v246, s50, v244
	s_waitcnt lgkmcnt(4)
	s_waitcnt lgkmcnt(3)
	v_mfma_f32_16x16x32_bf16 v[112:115], v[192:195], v[224:227], v[112:115]
	v_mfma_f32_16x16x32_bf16 v[120:123], v[196:199], v[224:227], v[120:123]
	v_mfma_f32_16x16x32_bf16 v[96:99], v[200:203], v[224:227], v[96:99]
	v_mfma_f32_16x16x32_bf16 v[104:107], v[204:207], v[224:227], v[104:107]
	s_add_u32 m0, s51, s48
	s_nop 0
	global_load_lds_dwordx4 v248, s[64:65]
	s_add_u32 s64, s64, 0x80
	s_addc_u32 s65, s65, 0
	ds_read_b128 v[224:227], v245 offset:8192
	ds_read_b128 v[208:211], v246
	s_waitcnt lgkmcnt(4)
	v_mfma_f32_16x16x32_bf16 v[116:119], v[192:195], v[228:231], v[116:119]
	v_mfma_f32_16x16x32_bf16 v[124:127], v[196:199], v[228:231], v[124:127]
	v_mfma_f32_16x16x32_bf16 v[100:103], v[200:203], v[228:231], v[100:103]
	v_mfma_f32_16x16x32_bf16 v[108:111], v[204:207], v[228:231], v[108:111]
	s_add_u32 s53, s51, s48
	s_add_u32 m0, s53, 0x2000
	s_nop 0
	global_load_lds_dwordx4 v248, s[66:67]
	s_add_u32 s66, s66, 0x80
	s_addc_u32 s67, s67, 0
	ds_read_b128 v[228:231], v245 offset:10240
	ds_read_b128 v[212:215], v246 offset:2048
	s_waitcnt lgkmcnt(5)
	v_mfma_f32_16x16x32_bf16 v[80:83], v[192:195], v[232:235], v[80:83]
	v_mfma_f32_16x16x32_bf16 v[88:91], v[196:199], v[232:235], v[88:91]
	v_mfma_f32_16x16x32_bf16 v[64:67], v[200:203], v[232:235], v[64:67]
	v_mfma_f32_16x16x32_bf16 v[72:75], v[204:207], v[232:235], v[72:75]
	s_add_u32 s53, s51, s48
	s_add_u32 m0, s53, 0x4000
	s_nop 0
	global_load_lds_dwordx4 v248, s[68:69]
	s_add_u32 s68, s68, 0x80
	s_addc_u32 s69, s69, 0
	ds_read_b128 v[232:235], v245 offset:12288
	ds_read_b128 v[216:219], v246 offset:4096
	s_waitcnt lgkmcnt(6)
	v_mfma_f32_16x16x32_bf16 v[84:87], v[192:195], v[236:239], v[84:87]
	v_mfma_f32_16x16x32_bf16 v[92:95], v[196:199], v[236:239], v[92:95]
	v_mfma_f32_16x16x32_bf16 v[68:71], v[200:203], v[236:239], v[68:71]
	v_mfma_f32_16x16x32_bf16 v[76:79], v[204:207], v[236:239], v[76:79]
	s_add_u32 s53, s51, s48
	s_add_u32 m0, s53, 0x6000
	s_nop 0
	global_load_lds_dwordx4 v248, s[70:71]
	s_add_u32 s70, s70, 0x80
	s_addc_u32 s71, s71, 0
	ds_read_b128 v[236:239], v245 offset:14336
	ds_read_b128 v[220:223], v246 offset:6144
	v_add_u32_e32 v245, s49, v241
	s_waitcnt lgkmcnt(7)
	v_mfma_f32_16x16x32_bf16 v[48:51], v[192:195], v[224:227], v[48:51]
	v_mfma_f32_16x16x32_bf16 v[56:59], v[196:199], v[224:227], v[56:59]
	v_mfma_f32_16x16x32_bf16 v[32:35], v[200:203], v[224:227], v[32:35]
	v_mfma_f32_16x16x32_bf16 v[40:43], v[204:207], v[224:227], v[40:43]
	ds_read_b128 v[224:227], v245
	s_waitcnt lgkmcnt(6)
	v_mfma_f32_16x16x32_bf16 v[52:55], v[192:195], v[228:231], v[52:55]
	v_mfma_f32_16x16x32_bf16 v[60:63], v[196:199], v[228:231], v[60:63]
	v_mfma_f32_16x16x32_bf16 v[36:39], v[200:203], v[228:231], v[36:39]
	v_mfma_f32_16x16x32_bf16 v[44:47], v[204:207], v[228:231], v[44:47]
	ds_read_b128 v[228:231], v245 offset:2048
	s_waitcnt lgkmcnt(5)
	v_mfma_f32_16x16x32_bf16 v[16:19], v[192:195], v[232:235], v[16:19]
	v_mfma_f32_16x16x32_bf16 v[24:27], v[196:199], v[232:235], v[24:27]
	v_mfma_f32_16x16x32_bf16 v[0:3], v[200:203], v[232:235], v[0:3]
	v_mfma_f32_16x16x32_bf16 v[8:11], v[204:207], v[232:235], v[8:11]
	ds_read_b128 v[232:235], v245 offset:4096
	s_waitcnt lgkmcnt(4)
	v_mfma_f32_16x16x32_bf16 v[20:23], v[192:195], v[236:239], v[20:23]
	v_mfma_f32_16x16x32_bf16 v[28:31], v[196:199], v[236:239], v[28:31]
	v_mfma_f32_16x16x32_bf16 v[4:7], v[200:203], v[236:239], v[4:7]
	v_mfma_f32_16x16x32_bf16 v[12:15], v[204:207], v[236:239], v[12:15]
	ds_read_b128 v[236:239], v245 offset:6144
	s_waitcnt lgkmcnt(4)
	s_waitcnt lgkmcnt(3)
	v_mfma_f32_16x16x32_bf16 v[112:115], v[208:211], v[224:227], v[112:115]
	v_mfma_f32_16x16x32_bf16 v[120:123], v[212:215], v[224:227], v[120:123]
	v_mfma_f32_16x16x32_bf16 v[96:99], v[216:219], v[224:227], v[96:99]
	v_mfma_f32_16x16x32_bf16 v[104:107], v[220:223], v[224:227], v[104:107]
	ds_read_b128 v[224:227], v245 offset:8192
	s_waitcnt lgkmcnt(3)
	v_mfma_f32_16x16x32_bf16 v[116:119], v[208:211], v[228:231], v[116:119]
	v_mfma_f32_16x16x32_bf16 v[124:127], v[212:215], v[228:231], v[124:127]
	v_mfma_f32_16x16x32_bf16 v[100:103], v[216:219], v[228:231], v[100:103]
	v_mfma_f32_16x16x32_bf16 v[108:111], v[220:223], v[228:231], v[108:111]
	ds_read_b128 v[228:231], v245 offset:10240
	s_waitcnt lgkmcnt(3)
	v_mfma_f32_16x16x32_bf16 v[80:83], v[208:211], v[232:235], v[80:83]
	v_mfma_f32_16x16x32_bf16 v[88:91], v[212:215], v[232:235], v[88:91]
	v_mfma_f32_16x16x32_bf16 v[64:67], v[216:219], v[232:235], v[64:67]
	v_mfma_f32_16x16x32_bf16 v[72:75], v[220:223], v[232:235], v[72:75]
	ds_read_b128 v[232:235], v245 offset:12288
	s_waitcnt lgkmcnt(3)
	v_mfma_f32_16x16x32_bf16 v[84:87], v[208:211], v[236:239], v[84:87]
	v_mfma_f32_16x16x32_bf16 v[92:95], v[212:215], v[236:239], v[92:95]
	v_mfma_f32_16x16x32_bf16 v[68:71], v[216:219], v[236:239], v[68:71]
	v_mfma_f32_16x16x32_bf16 v[76:79], v[220:223], v[236:239], v[76:79]
	ds_read_b128 v[236:239], v245 offset:14336
	s_waitcnt lgkmcnt(3)
	v_mfma_f32_16x16x32_bf16 v[48:51], v[208:211], v[224:227], v[48:51]
	v_mfma_f32_16x16x32_bf16 v[56:59], v[212:215], v[224:227], v[56:59]
	v_mfma_f32_16x16x32_bf16 v[32:35], v[216:219], v[224:227], v[32:35]
	v_mfma_f32_16x16x32_bf16 v[40:43], v[220:223], v[224:227], v[40:43]
	s_waitcnt lgkmcnt(2)
	v_mfma_f32_16x16x32_bf16 v[52:55], v[208:211], v[228:231], v[52:55]
	v_mfma_f32_16x16x32_bf16 v[60:63], v[212:215], v[228:231], v[60:63]
	v_mfma_f32_16x16x32_bf16 v[36:39], v[216:219], v[228:231], v[36:39]
	v_mfma_f32_16x16x32_bf16 v[44:47], v[220:223], v[228:231], v[44:47]
	s_waitcnt lgkmcnt(0)
	s_add_u32 s28, s28, 0x80
	s_addc_u32 s29, s29, 0
	s_add_u32 s49, s49, 0x10000
	s_sub_u32 s53, s49, 0x28000
	s_cmp_ge_u32 s49, 0x28000
	s_cselect_b32 s49, s53, s49
	s_mov_b32 s50, s51
	s_waitcnt vmcnt(0)
	s_barrier
	s_barrier
	v_add_u32_e32 v246, s50, v243
	v_add_u32_e32 v245, s49, v240
	ds_read_b128 v[192:195], v246
	ds_read_b128 v[196:199], v246 offset:2048
	ds_read_b128 v[200:203], v246 offset:4096
	ds_read_b128 v[204:207], v246 offset:6144
	ds_read_b128 v[224:227], v245
	ds_read_b128 v[228:231], v245 offset:2048
	v_mfma_f32_16x16x32_bf16 v[16:19], v[208:211], v[232:235], v[16:19]
	v_mfma_f32_16x16x32_bf16 v[24:27], v[212:215], v[232:235], v[24:27]
	v_mfma_f32_16x16x32_bf16 v[0:3], v[216:219], v[232:235], v[0:3]
	v_mfma_f32_16x16x32_bf16 v[8:11], v[220:223], v[232:235], v[8:11]
	ds_read_b128 v[232:235], v245 offset:4096
	v_mfma_f32_16x16x32_bf16 v[20:23], v[208:211], v[236:239], v[20:23]
	v_mfma_f32_16x16x32_bf16 v[28:31], v[212:215], v[236:239], v[28:31]
	v_mfma_f32_16x16x32_bf16 v[4:7], v[216:219], v[236:239], v[4:7]
	v_mfma_f32_16x16x32_bf16 v[12:15], v[220:223], v[236:239], v[12:15]
	ds_read_b128 v[236:239], v245 offset:6144
	v_add_u32_e32 v246, s50, v244
	s_waitcnt lgkmcnt(4)
	s_waitcnt lgkmcnt(3)
	v_mfma_f32_16x16x32_bf16 v[112:115], v[192:195], v[224:227], v[112:115]
	v_mfma_f32_16x16x32_bf16 v[120:123], v[196:199], v[224:227], v[120:123]
	v_mfma_f32_16x16x32_bf16 v[96:99], v[200:203], v[224:227], v[96:99]
	v_mfma_f32_16x16x32_bf16 v[104:107], v[204:207], v[224:227], v[104:107]
	ds_read_b128 v[224:227], v245 offset:8192
	ds_read_b128 v[208:211], v246
	s_waitcnt lgkmcnt(4)
	v_mfma_f32_16x16x32_bf16 v[116:119], v[192:195], v[228:231], v[116:119]
	v_mfma_f32_16x16x32_bf16 v[124:127], v[196:199], v[228:231], v[124:127]
	v_mfma_f32_16x16x32_bf16 v[100:103], v[200:203], v[228:231], v[100:103]
	v_mfma_f32_16x16x32_bf16 v[108:111], v[204:207], v[228:231], v[108:111]
	ds_read_b128 v[228:231], v245 offset:10240
	ds_read_b128 v[212:215], v246 offset:2048
	s_waitcnt lgkmcnt(5)
	v_mfma_f32_16x16x32_bf16 v[80:83], v[192:195], v[232:235], v[80:83]
	v_mfma_f32_16x16x32_bf16 v[88:91], v[196:199], v[232:235], v[88:91]
	v_mfma_f32_16x16x32_bf16 v[64:67], v[200:203], v[232:235], v[64:67]
	v_mfma_f32_16x16x32_bf16 v[72:75], v[204:207], v[232:235], v[72:75]
	ds_read_b128 v[232:235], v245 offset:12288
	ds_read_b128 v[216:219], v246 offset:4096
	s_waitcnt lgkmcnt(6)
	v_mfma_f32_16x16x32_bf16 v[84:87], v[192:195], v[236:239], v[84:87]
	v_mfma_f32_16x16x32_bf16 v[92:95], v[196:199], v[236:239], v[92:95]
	v_mfma_f32_16x16x32_bf16 v[68:71], v[200:203], v[236:239], v[68:71]
	v_mfma_f32_16x16x32_bf16 v[76:79], v[204:207], v[236:239], v[76:79]
	ds_read_b128 v[236:239], v245 offset:14336
	ds_read_b128 v[220:223], v246 offset:6144
	v_add_u32_e32 v245, s49, v241
	s_waitcnt lgkmcnt(7)
	v_mfma_f32_16x16x32_bf16 v[48:51], v[192:195], v[224:227], v[48:51]
	v_mfma_f32_16x16x32_bf16 v[56:59], v[196:199], v[224:227], v[56:59]
	v_mfma_f32_16x16x32_bf16 v[32:35], v[200:203], v[224:227], v[32:35]
	v_mfma_f32_16x16x32_bf16 v[40:43], v[204:207], v[224:227], v[40:43]
	ds_read_b128 v[224:227], v245
	s_waitcnt lgkmcnt(6)
	v_mfma_f32_16x16x32_bf16 v[52:55], v[192:195], v[228:231], v[52:55]
	v_mfma_f32_16x16x32_bf16 v[60:63], v[196:199], v[228:231], v[60:63]
	v_mfma_f32_16x16x32_bf16 v[36:39], v[200:203], v[228:231], v[36:39]
	v_mfma_f32_16x16x32_bf16 v[44:47], v[204:207], v[228:231], v[44:47]
	ds_read_b128 v[228:231], v245 offset:2048
	s_waitcnt lgkmcnt(5)
	v_mfma_f32_16x16x32_bf16 v[16:19], v[192:195], v[232:235], v[16:19]
	v_mfma_f32_16x16x32_bf16 v[24:27], v[196:199], v[232:235], v[24:27]
	v_mfma_f32_16x16x32_bf16 v[0:3], v[200:203], v[232:235], v[0:3]
	v_mfma_f32_16x16x32_bf16 v[8:11], v[204:207], v[232:235], v[8:11]
	ds_read_b128 v[232:235], v245 offset:4096
	s_waitcnt lgkmcnt(4)
	v_mfma_f32_16x16x32_bf16 v[20:23], v[192:195], v[236:239], v[20:23]
	v_mfma_f32_16x16x32_bf16 v[28:31], v[196:199], v[236:239], v[28:31]
	v_mfma_f32_16x16x32_bf16 v[4:7], v[200:203], v[236:239], v[4:7]
	v_mfma_f32_16x16x32_bf16 v[12:15], v[204:207], v[236:239], v[12:15]
	ds_read_b128 v[236:239], v245 offset:6144
	s_waitcnt lgkmcnt(4)
	s_waitcnt lgkmcnt(3)
	v_mfma_f32_16x16x32_bf16 v[112:115], v[208:211], v[224:227], v[112:115]
	v_mfma_f32_16x16x32_bf16 v[120:123], v[212:215], v[224:227], v[120:123]
	v_mfma_f32_16x16x32_bf16 v[96:99], v[216:219], v[224:227], v[96:99]
	v_mfma_f32_16x16x32_bf16 v[104:107], v[220:223], v[224:227], v[104:107]
	ds_read_b128 v[224:227], v245 offset:8192
	s_waitcnt lgkmcnt(3)
	v_mfma_f32_16x16x32_bf16 v[116:119], v[208:211], v[228:231], v[116:119]
	v_mfma_f32_16x16x32_bf16 v[124:127], v[212:215], v[228:231], v[124:127]
	v_mfma_f32_16x16x32_bf16 v[100:103], v[216:219], v[228:231], v[100:103]
	v_mfma_f32_16x16x32_bf16 v[108:111], v[220:223], v[228:231], v[108:111]
	ds_read_b128 v[228:231], v245 offset:10240
	s_waitcnt lgkmcnt(3)
	v_mfma_f32_16x16x32_bf16 v[80:83], v[208:211], v[232:235], v[80:83]
	v_mfma_f32_16x16x32_bf16 v[88:91], v[212:215], v[232:235], v[88:91]
	v_mfma_f32_16x16x32_bf16 v[64:67], v[216:219], v[232:235], v[64:67]
	v_mfma_f32_16x16x32_bf16 v[72:75], v[220:223], v[232:235], v[72:75]
	ds_read_b128 v[232:235], v245 offset:12288
	s_waitcnt lgkmcnt(3)
	v_mfma_f32_16x16x32_bf16 v[84:87], v[208:211], v[236:239], v[84:87]
	v_mfma_f32_16x16x32_bf16 v[92:95], v[212:215], v[236:239], v[92:95]
	v_mfma_f32_16x16x32_bf16 v[68:71], v[216:219], v[236:239], v[68:71]
	v_mfma_f32_16x16x32_bf16 v[76:79], v[220:223], v[236:239], v[76:79]
	ds_read_b128 v[236:239], v245 offset:14336
	s_waitcnt lgkmcnt(3)
	v_mfma_f32_16x16x32_bf16 v[48:51], v[208:211], v[224:227], v[48:51]
	v_mfma_f32_16x16x32_bf16 v[56:59], v[212:215], v[224:227], v[56:59]
	v_mfma_f32_16x16x32_bf16 v[32:35], v[216:219], v[224:227], v[32:35]
	v_mfma_f32_16x16x32_bf16 v[40:43], v[220:223], v[224:227], v[40:43]
	s_waitcnt lgkmcnt(2)
	v_mfma_f32_16x16x32_bf16 v[52:55], v[208:211], v[228:231], v[52:55]
	v_mfma_f32_16x16x32_bf16 v[60:63], v[212:215], v[228:231], v[60:63]
	v_mfma_f32_16x16x32_bf16 v[36:39], v[216:219], v[228:231], v[36:39]
	v_mfma_f32_16x16x32_bf16 v[44:47], v[220:223], v[228:231], v[44:47]
	s_waitcnt lgkmcnt(0)
	s_waitcnt vmcnt(0)
	s_barrier
	s_barrier
	v_mfma_f32_16x16x32_bf16 v[16:19], v[208:211], v[232:235], v[16:19]
	v_mfma_f32_16x16x32_bf16 v[24:27], v[212:215], v[232:235], v[24:27]
	v_mfma_f32_16x16x32_bf16 v[0:3], v[216:219], v[232:235], v[0:3]
	v_mfma_f32_16x16x32_bf16 v[8:11], v[220:223], v[232:235], v[8:11]
	v_mfma_f32_16x16x32_bf16 v[20:23], v[208:211], v[236:239], v[20:23]
	v_mfma_f32_16x16x32_bf16 v[28:31], v[212:215], v[236:239], v[28:31]
	v_mfma_f32_16x16x32_bf16 v[4:7], v[216:219], v[236:239], v[4:7]
	v_mfma_f32_16x16x32_bf16 v[12:15], v[220:223], v[236:239], v[12:15]
	s_nop 15
	v_permlane16_swap_b32_e32 v112, v116
	v_permlane16_swap_b32_e32 v113, v117
	v_permlane16_swap_b32_e32 v114, v118
	v_permlane16_swap_b32_e32 v115, v119
	v_permlane16_swap_b32_e32 v120, v124
	v_permlane16_swap_b32_e32 v121, v125
	v_permlane16_swap_b32_e32 v122, v126
	v_permlane16_swap_b32_e32 v123, v127
	v_permlane16_swap_b32_e32 v96, v100
	v_permlane16_swap_b32_e32 v97, v101
	v_permlane16_swap_b32_e32 v98, v102
	v_permlane16_swap_b32_e32 v99, v103
	v_permlane16_swap_b32_e32 v104, v108
	v_permlane16_swap_b32_e32 v105, v109
	v_permlane16_swap_b32_e32 v106, v110
	v_permlane16_swap_b32_e32 v107, v111
	v_permlane16_swap_b32_e32 v80, v84
	v_permlane16_swap_b32_e32 v81, v85
	v_permlane16_swap_b32_e32 v82, v86
	v_permlane16_swap_b32_e32 v83, v87
	v_permlane16_swap_b32_e32 v88, v92
	v_permlane16_swap_b32_e32 v89, v93
	v_permlane16_swap_b32_e32 v90, v94
	v_permlane16_swap_b32_e32 v91, v95
	v_permlane16_swap_b32_e32 v64, v68
	v_permlane16_swap_b32_e32 v65, v69
	v_permlane16_swap_b32_e32 v66, v70
	v_permlane16_swap_b32_e32 v67, v71
	v_permlane16_swap_b32_e32 v72, v76
	v_permlane16_swap_b32_e32 v73, v77
	v_permlane16_swap_b32_e32 v74, v78
	v_permlane16_swap_b32_e32 v75, v79
	v_permlane16_swap_b32_e32 v48, v52
	v_permlane16_swap_b32_e32 v49, v53
	v_permlane16_swap_b32_e32 v50, v54
	v_permlane16_swap_b32_e32 v51, v55
	v_permlane16_swap_b32_e32 v56, v60
	v_permlane16_swap_b32_e32 v57, v61
	v_permlane16_swap_b32_e32 v58, v62
	v_permlane16_swap_b32_e32 v59, v63
	v_permlane16_swap_b32_e32 v32, v36
	v_permlane16_swap_b32_e32 v33, v37
	v_permlane16_swap_b32_e32 v34, v38
	v_permlane16_swap_b32_e32 v35, v39
	v_permlane16_swap_b32_e32 v40, v44
	v_permlane16_swap_b32_e32 v41, v45
	v_permlane16_swap_b32_e32 v42, v46
	v_permlane16_swap_b32_e32 v43, v47
	v_permlane16_swap_b32_e32 v16, v20
	v_permlane16_swap_b32_e32 v17, v21
	v_permlane16_swap_b32_e32 v18, v22
	v_permlane16_swap_b32_e32 v19, v23
	v_permlane16_swap_b32_e32 v24, v28
	v_permlane16_swap_b32_e32 v25, v29
	v_permlane16_swap_b32_e32 v26, v30
	v_permlane16_swap_b32_e32 v27, v31
	v_permlane16_swap_b32_e32 v0, v4
	v_permlane16_swap_b32_e32 v1, v5
	v_permlane16_swap_b32_e32 v2, v6
	v_permlane16_swap_b32_e32 v3, v7
	v_permlane16_swap_b32_e32 v8, v12
	v_permlane16_swap_b32_e32 v9, v13
	v_permlane16_swap_b32_e32 v10, v14
	v_permlane16_swap_b32_e32 v11, v15
	v_permlane32_swap_b32_e32 v112, v116
	v_permlane32_swap_b32_e32 v113, v117
	v_permlane32_swap_b32_e32 v114, v118
	v_permlane32_swap_b32_e32 v115, v119
	v_permlane32_swap_b32_e32 v120, v124
	v_permlane32_swap_b32_e32 v121, v125
	v_permlane32_swap_b32_e32 v122, v126
	v_permlane32_swap_b32_e32 v123, v127
	v_permlane32_swap_b32_e32 v96, v100
	v_permlane32_swap_b32_e32 v97, v101
	v_permlane32_swap_b32_e32 v98, v102
	v_permlane32_swap_b32_e32 v99, v103
	v_permlane32_swap_b32_e32 v104, v108
	v_permlane32_swap_b32_e32 v105, v109
	v_permlane32_swap_b32_e32 v106, v110
	v_permlane32_swap_b32_e32 v107, v111
	v_permlane32_swap_b32_e32 v80, v84
	v_permlane32_swap_b32_e32 v81, v85
	v_permlane32_swap_b32_e32 v82, v86
	v_permlane32_swap_b32_e32 v83, v87
	v_permlane32_swap_b32_e32 v88, v92
	v_permlane32_swap_b32_e32 v89, v93
	v_permlane32_swap_b32_e32 v90, v94
	v_permlane32_swap_b32_e32 v91, v95
	v_permlane32_swap_b32_e32 v64, v68
	v_permlane32_swap_b32_e32 v65, v69
	v_permlane32_swap_b32_e32 v66, v70
	v_permlane32_swap_b32_e32 v67, v71
	v_permlane32_swap_b32_e32 v72, v76
	v_permlane32_swap_b32_e32 v73, v77
	v_permlane32_swap_b32_e32 v74, v78
	v_permlane32_swap_b32_e32 v75, v79
	v_permlane32_swap_b32_e32 v48, v52
	v_permlane32_swap_b32_e32 v49, v53
	v_permlane32_swap_b32_e32 v50, v54
	v_permlane32_swap_b32_e32 v51, v55
	v_permlane32_swap_b32_e32 v56, v60
	v_permlane32_swap_b32_e32 v57, v61
	v_permlane32_swap_b32_e32 v58, v62
	v_permlane32_swap_b32_e32 v59, v63
	v_permlane32_swap_b32_e32 v32, v36
	v_permlane32_swap_b32_e32 v33, v37
	v_permlane32_swap_b32_e32 v34, v38
	v_permlane32_swap_b32_e32 v35, v39
	v_permlane32_swap_b32_e32 v40, v44
	v_permlane32_swap_b32_e32 v41, v45
	v_permlane32_swap_b32_e32 v42, v46
	v_permlane32_swap_b32_e32 v43, v47
	v_permlane32_swap_b32_e32 v16, v20
	v_permlane32_swap_b32_e32 v17, v21
	v_permlane32_swap_b32_e32 v18, v22
	v_permlane32_swap_b32_e32 v19, v23
	v_permlane32_swap_b32_e32 v24, v28
	v_permlane32_swap_b32_e32 v25, v29
	v_permlane32_swap_b32_e32 v26, v30
	v_permlane32_swap_b32_e32 v27, v31
	v_permlane32_swap_b32_e32 v0, v4
	v_permlane32_swap_b32_e32 v1, v5
	v_permlane32_swap_b32_e32 v2, v6
	v_permlane32_swap_b32_e32 v3, v7
	v_permlane32_swap_b32_e32 v8, v12
	v_permlane32_swap_b32_e32 v9, v13
	v_permlane32_swap_b32_e32 v10, v14
	v_permlane32_swap_b32_e32 v11, v15
	s_nop 1
